# MLA / diff tile loops unrolled 4x with static LDS slot addressing (base registers + immediates: no per-tile address VALU), row-sum without moves
# speedup vs baseline: 1.0182x; 1.0099x over previous
; template <int DQK, int DV, int FLAGS, int qp, int kp, int vts, int op> ...
;     ...
;     u32x4 kreg[KPT], vreg[VPT];
;     unsigned kgo[KPT], vgo[VPT], klo[KPT], vlo[VPT];
; #pragma unroll
;     for (int i = 0; i < KPT; ++i) { const int c = tid + i * NTHREADS; const int row = c / KC, cc = c % KC; kgo[i] = (unsigned)(row * kp + cc * 8) * 2u; klo[i] = (unsigned)(row * KROW + cc * 16); }
; #pragma unroll
;     for (int i = 0; i < VPT; ++i) { const int c = tid + i * NTHREADS; const int d = c >> 3, cc = c & 7; vgo[i] = (unsigned)(d * vts + cc * 8) * 2u; vlo[i] = (unsigned)(KT_BYTES + d * VROW + cc * 16); }
;     ...
;     ATT_GLOAD((FLAGS & AF_REV) ? kt_hi - 1 : kt_lo); ATT_LSTORE(0);
;     __syncthreads();
;     bool started = false;
;     const int prow = (r32 & ~12) | ((r32 & 4) << 1) | ((r32 & 8) >> 1);
;     const int ntile = kt_hi - kt_lo;
;     for (int it = 0; it < ntile; ++it) {
;         const int t = (FLAGS & AF_REV) ? kt_hi - 1 - it : kt_lo + it;
;         const int cur = it & 1;
;         const bool more = (it + 1 < ntile);
;         const int kv0 = t * 64;
;         bool skip = false;
;         if (FLAGS & AF_CAUSAL) skip = skip || (kv0 > qmax_w);
;         if (FLAGS & AF_WINDOW) skip = skip || (kv0 + 63 < qmin_w - (SWA_W - 1));
;         if (!skip) {
;             const LAS unsigned char* kb = lds + cur * BUF + prow * KROW + 16 * hi;
;             const LAS unsigned char* vb = lds + cur * BUF + KT_BYTES + r32 * VROW + 16 * hi;
;             f32x16 p0, p1;
;             bf16x8 kf[2][4];
; #pragma unroll
;             for (int i = 0; i < 2; ++i) { kf[0][2 * i] = *(const LAS bf16x8*)(kb + i * 32); kf[0][2 * i + 1] = *(const LAS bf16x8*)(kb + 32 * KROW + i * 32); }
;             const int nrel = qpos - kv0 - 8 * hi;
;             if (FLAGS & AF_ALIBI) { const float ab = -slope2 * (float)nrel - ((FLAGS & AF_ROBUST) ? 0.f : m);
; #pragma unroll
;                 for (int r = 0; r < 16; ++r) { const float c = (float)(16 * (r >> 3) + (r & 7)); p0[r] = __builtin_fmaf(slope2, c, ab); p1[r] = __builtin_fmaf(slope2, c + 32.f, ab); }
;             } else if (FLAGS & AF_ROBUST) {
; #pragma unroll
;                 for (int r = 0; r < 16; ++r) { p0[r] = 0.f; p1[r] = 0.f; }
;             } else { p0 = negm; p1 = negm; }
;             __builtin_amdgcn_sched_barrier(0);
; #pragma unroll
;             for (int c = 0; c < ND0 / 2; ++c) {
;                 if (c + 1 < ND0 / 2) {
.LBB0_536:
	s_andn2_b64 vcc, exec, s[12:13]
	v_lshlrev_b32_e32 v170, 3, v19
	s_cbranch_vccnz .LBB0_524
	s_and_b32 s87, s19, 0xffffffe0
	s_add_i32 s16, s16, s17
	s_add_i32 s87, s87, s3
	s_lshl_b32 s15, s2, 2
	s_lshl_b32 s12, s16, 17
	s_or_b32 s88, s87, 31
	s_add_i32 s2, s15, 4
	s_bfe_u32 s17, s16, 0x30004
	s_and_b32 s12, s12, 0xe00000
	s_add_u32 s12, s14, s12
	s_addc_u32 s13, 0, 0
	s_add_u32 s12, s93, s12
	v_readlane_b32 s14, v252, 61
	v_mov_b32_e32 v21, v1
	s_addc_u32 s13, s14, s13
	s_mulk_i32 s17, 0xc0
	v_and_b32_e32 v22, 31, v17
	v_and_b32_e32 v19, 19, v17
	v_lshlrev_b32_e32 v23, 1, v17
	v_lshrrev_b32_e32 v17, 1, v17
	v_lshl_add_u64 v[176:177], s[12:13], 0, v[20:21]
	s_add_u32 s12, s18, s17
	v_and_b32_e32 v23, 8, v23
	v_and_b32_e32 v17, 4, v17
	s_addc_u32 s13, 0, 0
	v_readlane_b32 s14, v252, 63
	v_or3_b32 v17, v19, v23, v17
	s_add_u32 s12, s14, s12
	v_readlane_b32 s14, v253, 1
	v_mul_u32_u24_e32 v169, 0xd0, v17
	v_mul_u32_u24_e32 v171, 0x90, v22
	v_mov_b32_e32 v17, v1
	v_mov_b32_e32 v19, v1
	v_add_u32_e32 v22, s87, v22
	s_addc_u32 s13, s14, s13
	v_mov_b32_e32 v32, v1
	v_mov_b32_e32 v33, v1
	v_sub_u32_e32 v173, v22, v170
	v_lshl_add_u64 v[178:179], s[12:13], 0, v[16:17]
	v_lshl_add_u64 v[180:181], s[12:13], 0, v[18:19]
	v_mov_b32_e32 v34, v1
	v_mov_b32_e32 v35, v1
	v_mov_b32_e32 v36, v1
	v_mov_b32_e32 v37, v1
	v_mov_b32_e32 v38, v1
	v_mov_b32_e32 v39, v1
	v_mov_b32_e32 v40, v1
	v_mov_b32_e32 v41, v1
	v_mov_b32_e32 v42, v1
	v_mov_b32_e32 v43, v1
	v_mov_b32_e32 v44, v1
	v_mov_b32_e32 v45, v1
	v_mov_b32_e32 v46, v1
	v_mov_b32_e32 v47, v1
	v_mov_b32_e32 v183, 0
	v_mov_b64_e32 v[16:17], v[32:33]
	s_mov_b64 s[0:1], s[90:91]
	s_mov_b32 s3, 1
	s_xor_b32 s90, s15, -4
	s_mov_b64 s[82:83], 0
	s_mov_b32 s91, 63
	v_mov_b64_e32 v[18:19], v[34:35]
	v_mov_b64_e32 v[20:21], v[36:37]
	v_mov_b64_e32 v[22:23], v[38:39]
	v_mov_b64_e32 v[24:25], v[40:41]
	v_mov_b64_e32 v[26:27], v[42:43]
	v_mov_b64_e32 v[28:29], v[44:45]
	v_mov_b64_e32 v[30:31], v[46:47]
	v_mov_b32_e32 v175, 0
	v_mov_b32_e32 v48, 0
	v_mov_b32_e32 v49, v183
	v_mov_b32_e32 v50, v183
	v_mov_b32_e32 v51, v183
	v_mov_b32_e32 v52, v183
	v_mov_b32_e32 v53, v183
	v_mov_b32_e32 v54, v183
	v_mov_b32_e32 v55, v183
	v_mov_b32_e32 v56, v183
	v_mov_b32_e32 v57, v183
	v_mov_b32_e32 v58, v183
	v_mov_b32_e32 v59, v183
	v_mov_b32_e32 v60, v183
	v_mov_b32_e32 v61, v183
	v_mov_b32_e32 v62, v183
	v_mov_b32_e32 v63, v183
	s_andn2_b64 vcc, exec, s[4:5]
	s_cbranch_vccnz .Lq_fallback
	v_readfirstlane_b32 s98, v178
	v_readfirstlane_b32 s99, v179
	v_readfirstlane_b32 s100, v176
	v_readfirstlane_b32 s101, v177
	s_nop 1
	v_subrev_u32_e32 v178, s98, v178
	v_subrev_u32_e32 v180, s98, v180
	v_subrev_u32_e32 v176, s100, v176
	v_add_u32_e32 v187, v169, v0
	v_add_u32_e32 v213, 0xb000, v187
	v_add_u32_e32 v246, v171, v0
	v_add_u32_e32 v247, 0xb000, v246
	v_add_u32_e32 v248, 0xb000, v14
	v_add_u32_e32 v249, 0xb000, v174
	v_add_u32_e32 v250, 0xb000, v172
	s_movk_i32 s16, 0x5800
	s_waitcnt vmcnt(0)
	v_add_u32_e32 v209, s16, v14
	v_add_u32_e32 v210, s16, v174
	v_add_u32_e32 v211, s16, v172
	ds_write_b128 v209, v[214:217]
	ds_write_b128 v210, v[222:225] offset:13312
	s_and_saveexec_b64 s[14:15], s[10:11]
	ds_write_b128 v211, v[218:221]
	s_or_b64 exec, exec, s[14:15]
	s_add_u32 s98, s98, s96
	s_addc_u32 s99, s99, s97
	s_add_u32 s100, s100, 0x80
	s_addc_u32 s101, s101, 0
	s_and_saveexec_b64 s[14:15], s[10:11]
	global_load_dwordx4 v[144:147], v180, s[98:99]
	s_or_b64 exec, exec, s[14:15]
	global_load_dwordx4 v[140:143], v178, s[98:99]
	global_load_dwordx4 v[148:151], v176, s[100:101]
	s_add_u32 s98, s98, s96
	s_addc_u32 s99, s99, s97
	s_add_u32 s100, s100, 0x80
	s_addc_u32 s101, s101, 0
	s_lshr_b32 s20, s88, 6
	s_add_i32 s20, s20, 1
	s_min_i32 s20, s20, s2
	s_mov_b32 s3, 0
	s_waitcnt lgkmcnt(0)
	s_barrier
	v_add_u32_e32 v206, v169, v0
	ds_read_b128 v[96:99], v206 offset:0
	ds_read_b128 v[104:107], v206 offset:6656
	ds_read_b128 v[100:103], v206 offset:32
	ds_read_b128 v[108:111], v206 offset:6688
	ds_read_b128 v[112:115], v206 offset:64
	ds_read_b128 v[120:123], v206 offset:6720
	ds_read_b128 v[116:119], v206 offset:96
	ds_read_b128 v[124:127], v206 offset:6752
	s_waitcnt lgkmcnt(4)
	v_mfma_f32_32x32x16_bf16 v[64:79], v[96:99], v[2:5], v[48:63]
	v_mfma_f32_32x32x16_bf16 v[80:95], v[104:107], v[2:5], v[48:63]
	v_mfma_f32_32x32x16_bf16 v[64:79], v[100:103], v[6:9], v[64:79]
	v_mfma_f32_32x32x16_bf16 v[80:95], v[108:111], v[6:9], v[80:95]
	ds_read_b128 v[96:99], v206 offset:128
	ds_read_b128 v[104:107], v206 offset:6784
	ds_read_b128 v[100:103], v206 offset:160
	ds_read_b128 v[108:111], v206 offset:6816
	s_waitcnt lgkmcnt(4)
	v_mfma_f32_32x32x16_bf16 v[64:79], v[112:115], v[10:13], v[64:79]
	v_mfma_f32_32x32x16_bf16 v[80:95], v[120:123], v[10:13], v[80:95]
	v_mfma_f32_32x32x16_bf16 v[64:79], v[116:119], v[128:131], v[64:79]
	v_mfma_f32_32x32x16_bf16 v[80:95], v[124:127], v[128:131], v[80:95]
	s_waitcnt lgkmcnt(0)
	v_mfma_f32_32x32x16_bf16 v[64:79], v[96:99], v[132:135], v[64:79]
	v_mfma_f32_32x32x16_bf16 v[80:95], v[104:107], v[132:135], v[80:95]
	v_mfma_f32_32x32x16_bf16 v[64:79], v[100:103], v[136:139], v[64:79]
	v_mfma_f32_32x32x16_bf16 v[80:95], v[108:111], v[136:139], v[80:95]
.Lq_top0:
	s_cmp_eq_u32 s3, 0
	s_cbranch_scc1 .Lq_gen0
	s_add_i32 s13, s3, 1
	s_cmp_ge_i32 s13, s20
	s_cbranch_scc1 .Lq_gen0
	ds_read_b128 v[96:99], v187 offset:22528
	ds_read_b128 v[104:107], v187 offset:29184
	ds_read_b128 v[100:103], v187 offset:22560
	ds_read_b128 v[108:111], v187 offset:29216
	ds_read_b128 v[112:115], v187 offset:22592
	ds_read_b128 v[120:123], v187 offset:29248
	ds_read_b128 v[116:119], v187 offset:22624
	ds_read_b128 v[124:127], v187 offset:29280
	v_mfma_f32_32x32x16_bf16 v[32:47], v[152:155], v[214:217], v[32:47]
	v_exp_f32_e32 v64, v64
	v_exp_f32_e32 v65, v65
	v_mfma_f32_32x32x16_bf16 v[16:31], v[188:191], v[214:217], v[16:31]
	v_exp_f32_e32 v80, v80
	v_exp_f32_e32 v81, v81
	v_add_f32_e32 v204, v64, v175
	s_waitcnt vmcnt(0)
	ds_write_b128 v248, v[140:143] offset:0
	v_mfma_f32_32x32x16_bf16 v[32:47], v[156:159], v[218:221], v[32:47]
	v_exp_f32_e32 v66, v66
	v_exp_f32_e32 v67, v67
	v_add_f32_e32 v204, v80, v204
	v_add_f32_e32 v205, v65, v81
	ds_write_b128 v249, v[148:151] offset:13312
	v_mfma_f32_32x32x16_bf16 v[16:31], v[192:195], v[218:221], v[16:31]
	v_exp_f32_e32 v82, v82
	v_exp_f32_e32 v83, v83
	v_add_f32_e32 v204, v66, v204
	v_add_f32_e32 v205, v67, v205
	s_and_saveexec_b64 s[14:15], s[10:11]
	ds_write_b128 v250, v[144:147] offset:0
	s_or_b64 exec, exec, s[14:15]
	v_mfma_f32_32x32x16_bf16 v[32:47], v[160:163], v[222:225], v[32:47]
	v_exp_f32_e32 v68, v68
	v_exp_f32_e32 v69, v69
	v_add_f32_e32 v204, v82, v204
	v_add_f32_e32 v205, v83, v205
	s_add_i32 s12, s3, 3
	s_cmp_ge_i32 s12, s2
	s_cbranch_scc1 .Lq_ng0_s0
	s_and_saveexec_b64 s[14:15], s[10:11]
	global_load_dwordx4 v[144:147], v180, s[98:99]
	s_or_b64 exec, exec, s[14:15]

; #define LAS __attribute__((address_space(3)))
; template <int DQK, int DV, int FLAGS, int qp, int kp, int vts, int op> ...
;     ...
;             for (int c = 0; c < ND0 / 2; ++c) {
;                 if (c + 1 < ND0 / 2) {
; #pragma unroll
;                     for (int i = 0; i < 2; ++i) { kf[(c + 1) & 1][2 * i] = *(const LAS bf16x8*)(kb + (2 * c + 2 + i) * 32); kf[(c + 1) & 1][2 * i + 1] = *(const LAS bf16x8*)(kb + 32 * KROW + (2 * c + 2 + i) * 32); }
;                 }
; #pragma unroll
;                 for (int i = 0; i < 2; ++i) {
;                     p0 = __builtin_amdgcn_mfma_f32_32x32x16_bf16(kf[c & 1][2 * i], qr[2 * c + i], p0, 0, 0, 0);
;                     p1 = __builtin_amdgcn_mfma_f32_32x32x16_bf16(kf[c & 1][2 * i + 1], qr[2 * c + i], p1, 0, 0, 0);
;                 }
;                 __builtin_amdgcn_sched_barrier(0);
;             }
;     ...
;             for (int r = 0; r < 16; ++r) { p0[r] = __builtin_amdgcn_exp2f(p0[r]); p1[r] = __builtin_amdgcn_exp2f(p1[r]); }
; #pragma unroll
;             for (int r = 0; r < 16; r += 2) { rs2 += (f32x2){p0[r], p0[r + 1]}; rs2 += (f32x2){p1[r], p1[r + 1]}; }
;             l += rs2.x + rs2.y;
;             bf16x8 pf[4];
;             pf[0] = pack_bf16x8(p0, 0); pf[1] = pack_bf16x8(p0, 8); pf[2] = pack_bf16x8(p1, 0); pf[3] = pack_bf16x8(p1, 8);
;             __builtin_amdgcn_sched_barrier(0);
; #pragma unroll
;             for (int d = 0; d < NDB; ++d) {
;                 if (d + 1 < NDB) {
; #pragma unroll
;                     for (int ks = 0; ks < 4; ++ks) vf[(d + 1) & 1][ks] = *(const LAS bf16x8*)(vb + (d + 1) * 32 * VROW + ks * 32);
;                 }
; #pragma unroll
;                 for (int ks = 0; ks < 4; ++ks) o[d] = __builtin_amdgcn_mfma_f32_32x32x16_bf16(vf[d & 1][ks], pf[ks], o[d], 0, 0, 0);
;                 __builtin_amdgcn_sched_barrier(0);
;             }
.Lq_ng2_s0:
	v_mfma_f32_32x32x16_bf16 v[16:31], v[200:203], v[226:229], v[16:31]
	v_exp_f32_e32 v86, v86
	v_exp_f32_e32 v87, v87
	v_add_f32_e32 v204, v70, v204
	v_add_f32_e32 v205, v71, v205
	ds_read_b128 v[152:155], v246 offset:13312
	ds_read_b128 v[156:159], v246 offset:13344
	ds_read_b128 v[160:163], v246 offset:13376
	ds_read_b128 v[164:167], v246 offset:13408
	s_waitcnt lgkmcnt(8)
	v_mfma_f32_32x32x16_bf16 v[214:229], v[96:99], v[2:5], v[48:63]
	v_exp_f32_e32 v72, v72
	v_exp_f32_e32 v73, v73
	v_add_f32_e32 v204, v86, v204
	v_add_f32_e32 v205, v87, v205
	v_mfma_f32_32x32x16_bf16 v[230:245], v[104:107], v[2:5], v[48:63]
	v_exp_f32_e32 v88, v88
	v_exp_f32_e32 v89, v89
	v_add_f32_e32 v204, v72, v204
	v_add_f32_e32 v205, v73, v205
	v_mfma_f32_32x32x16_bf16 v[214:229], v[100:103], v[6:9], v[214:229]
	v_exp_f32_e32 v74, v74
	v_exp_f32_e32 v75, v75
	v_add_f32_e32 v204, v88, v204
	v_add_f32_e32 v205, v89, v205
	v_mfma_f32_32x32x16_bf16 v[230:245], v[108:111], v[6:9], v[230:245]
	v_exp_f32_e32 v90, v90
	v_exp_f32_e32 v91, v91
	v_add_f32_e32 v204, v74, v204
	v_add_f32_e32 v205, v75, v205
	ds_read_b128 v[96:99], v187 offset:22656
	ds_read_b128 v[104:107], v187 offset:29312
	ds_read_b128 v[100:103], v187 offset:22688
	ds_read_b128 v[108:111], v187 offset:29344
	s_waitcnt lgkmcnt(8)
	v_mfma_f32_32x32x16_bf16 v[214:229], v[112:115], v[10:13], v[214:229]
	v_exp_f32_e32 v76, v76
	v_exp_f32_e32 v77, v77
	v_add_f32_e32 v204, v90, v204
	v_add_f32_e32 v205, v91, v205
	v_mfma_f32_32x32x16_bf16 v[230:245], v[120:123], v[10:13], v[230:245]
	v_exp_f32_e32 v92, v92
	v_exp_f32_e32 v93, v93
	v_add_f32_e32 v204, v76, v204
	v_add_f32_e32 v205, v77, v205
	v_mfma_f32_32x32x16_bf16 v[214:229], v[116:119], v[128:131], v[214:229]
	v_exp_f32_e32 v78, v78
	v_exp_f32_e32 v79, v79
	v_add_f32_e32 v204, v92, v204
	v_add_f32_e32 v205, v93, v205
	v_mfma_f32_32x32x16_bf16 v[230:245], v[124:127], v[128:131], v[230:245]
	v_exp_f32_e32 v94, v94
	v_exp_f32_e32 v95, v95
	v_add_f32_e32 v204, v78, v204
	v_add_f32_e32 v205, v79, v205
	ds_read_b128 v[188:191], v246 offset:17920
	ds_read_b128 v[192:195], v246 offset:17952
	ds_read_b128 v[196:199], v246 offset:17984
	ds_read_b128 v[200:203], v246 offset:18016
	s_waitcnt lgkmcnt(4)
	v_mfma_f32_32x32x16_bf16 v[214:229], v[96:99], v[132:135], v[214:229]
	s_nop 0
	v_add_f32_e32 v204, v94, v204
	v_add_f32_e32 v205, v95, v205
	v_cvt_pk_bf16_f32 v64, v64, v65
	v_cvt_pk_bf16_f32 v65, v66, v67
	v_cvt_pk_bf16_f32 v66, v68, v69
	v_mfma_f32_32x32x16_bf16 v[230:245], v[104:107], v[132:135], v[230:245]
	v_cvt_pk_bf16_f32 v67, v70, v71
	v_cvt_pk_bf16_f32 v68, v72, v73
	v_cvt_pk_bf16_f32 v69, v74, v75
	v_cvt_pk_bf16_f32 v70, v76, v77
	v_cvt_pk_bf16_f32 v71, v78, v79
	v_mfma_f32_32x32x16_bf16 v[214:229], v[100:103], v[136:139], v[214:229]
	v_cvt_pk_bf16_f32 v72, v80, v81
	v_cvt_pk_bf16_f32 v73, v82, v83
	v_cvt_pk_bf16_f32 v74, v84, v85
	v_cvt_pk_bf16_f32 v75, v86, v87
	v_cvt_pk_bf16_f32 v76, v88, v89
	v_mfma_f32_32x32x16_bf16 v[230:245], v[108:111], v[136:139], v[230:245]
	v_cvt_pk_bf16_f32 v77, v90, v91
	v_cvt_pk_bf16_f32 v78, v92, v93
	v_cvt_pk_bf16_f32 v79, v94, v95
	v_add_f32_e32 v175, v204, v205
	s_branch .Lq_tailb0
.Lq_gen0:
	s_add_i32 s13, s3, 1
	s_cmp_ge_i32 s13, s20
	s_cbranch_scc1 .Lq_nokr_q0
	s_add_i32 s12, s3, 1
	s_and_b32 s12, s12, 3
	s_mulk_i32 s12, 0x5800
	v_add3_u32 v206, s12, v169, v0
	ds_read_b128 v[96:99], v206 offset:0
	ds_read_b128 v[104:107], v206 offset:6656
	ds_read_b128 v[100:103], v206 offset:32
	ds_read_b128 v[108:111], v206 offset:6688
	ds_read_b128 v[112:115], v206 offset:64
	ds_read_b128 v[120:123], v206 offset:6720
	ds_read_b128 v[116:119], v206 offset:96
	ds_read_b128 v[124:127], v206 offset:6752

; template <int DQK, int DV, int FLAGS, int qp, int kp, int vts, int op> ...
;     ...
;             f32x2 rs2 = {0.f, 0.f};
; #pragma unroll
;             for (int r = 0; r < 16; ++r) { p0[r] = __builtin_amdgcn_exp2f(p0[r]); p1[r] = __builtin_amdgcn_exp2f(p1[r]); }
; #pragma unroll
;             for (int r = 0; r < 16; r += 2) { rs2 += (f32x2){p0[r], p0[r + 1]}; rs2 += (f32x2){p1[r], p1[r + 1]}; }
;             l += rs2.x + rs2.y;
;             bf16x8 pf[4];
;             pf[0] = pack_bf16x8(p0, 0); pf[1] = pack_bf16x8(p0, 8); pf[2] = pack_bf16x8(p1, 0); pf[3] = pack_bf16x8(p1, 8);
.Lq_notfirst_q0:
	v_exp_f32_e32 v64, v64
	v_exp_f32_e32 v65, v65
	v_exp_f32_e32 v80, v80
	v_exp_f32_e32 v81, v81
	v_add_f32_e32 v204, v64, v175
	v_exp_f32_e32 v66, v66
	v_exp_f32_e32 v67, v67
	v_add_f32_e32 v204, v80, v204
	v_add_f32_e32 v205, v65, v81
	v_exp_f32_e32 v82, v82
	v_exp_f32_e32 v83, v83
	v_add_f32_e32 v204, v66, v204
	v_add_f32_e32 v205, v67, v205
	v_exp_f32_e32 v68, v68
	v_exp_f32_e32 v69, v69
	v_add_f32_e32 v204, v82, v204
	v_add_f32_e32 v205, v83, v205
	v_exp_f32_e32 v84, v84
	v_exp_f32_e32 v85, v85
	v_add_f32_e32 v204, v68, v204
	v_add_f32_e32 v205, v69, v205
	v_exp_f32_e32 v70, v70
	v_exp_f32_e32 v71, v71
	v_add_f32_e32 v204, v84, v204
	v_add_f32_e32 v205, v85, v205
	v_exp_f32_e32 v86, v86
	v_exp_f32_e32 v87, v87
	v_add_f32_e32 v204, v70, v204
	v_add_f32_e32 v205, v71, v205
	v_exp_f32_e32 v72, v72
	v_exp_f32_e32 v73, v73
	v_add_f32_e32 v204, v86, v204
	v_add_f32_e32 v205, v87, v205
	v_exp_f32_e32 v88, v88
	v_exp_f32_e32 v89, v89
	v_add_f32_e32 v204, v72, v204
	v_add_f32_e32 v205, v73, v205
	v_exp_f32_e32 v74, v74
	v_exp_f32_e32 v75, v75
	v_add_f32_e32 v204, v88, v204
	v_add_f32_e32 v205, v89, v205
	v_exp_f32_e32 v90, v90
	v_exp_f32_e32 v91, v91
	v_add_f32_e32 v204, v74, v204
	v_add_f32_e32 v205, v75, v205
	v_exp_f32_e32 v76, v76
	v_exp_f32_e32 v77, v77
	v_add_f32_e32 v204, v90, v204
	v_add_f32_e32 v205, v91, v205
	v_exp_f32_e32 v92, v92
	v_exp_f32_e32 v93, v93
	v_add_f32_e32 v204, v76, v204
	v_add_f32_e32 v205, v77, v205
	v_exp_f32_e32 v78, v78
	v_exp_f32_e32 v79, v79
	v_add_f32_e32 v204, v92, v204
	v_add_f32_e32 v205, v93, v205
	v_exp_f32_e32 v94, v94
	v_exp_f32_e32 v95, v95
	v_add_f32_e32 v204, v78, v204
	v_add_f32_e32 v205, v79, v205
	s_nop 0
	v_add_f32_e32 v204, v94, v204
	v_add_f32_e32 v205, v95, v205
	v_cvt_pk_bf16_f32 v64, v64, v65
	v_cvt_pk_bf16_f32 v65, v66, v67
	v_cvt_pk_bf16_f32 v66, v68, v69
	v_cvt_pk_bf16_f32 v67, v70, v71
	v_cvt_pk_bf16_f32 v68, v72, v73
	v_cvt_pk_bf16_f32 v69, v74, v75
	v_cvt_pk_bf16_f32 v70, v76, v77
	v_cvt_pk_bf16_f32 v71, v78, v79
	v_cvt_pk_bf16_f32 v72, v80, v81
	v_cvt_pk_bf16_f32 v73, v82, v83
	v_cvt_pk_bf16_f32 v74, v84, v85
	v_cvt_pk_bf16_f32 v75, v86, v87
	v_cvt_pk_bf16_f32 v76, v88, v89
	v_cvt_pk_bf16_f32 v77, v90, v91
	v_cvt_pk_bf16_f32 v78, v92, v93
	v_cvt_pk_bf16_f32 v79, v94, v95
	v_add_f32_e32 v175, v204, v205

; #define LAS __attribute__((address_space(3)))
; template <int DQK, int DV, int FLAGS, int qp, int kp, int vts, int op> ...
;     ...
;             for (int c = 0; c < ND0 / 2; ++c) {
;                 if (c + 1 < ND0 / 2) {
; #pragma unroll
;                     for (int i = 0; i < 2; ++i) { kf[(c + 1) & 1][2 * i] = *(const LAS bf16x8*)(kb + (2 * c + 2 + i) * 32); kf[(c + 1) & 1][2 * i + 1] = *(const LAS bf16x8*)(kb + 32 * KROW + (2 * c + 2 + i) * 32); }
;                 }
; #pragma unroll
;                 for (int i = 0; i < 2; ++i) {
;                     p0 = __builtin_amdgcn_mfma_f32_32x32x16_bf16(kf[c & 1][2 * i], qr[2 * c + i], p0, 0, 0, 0);
;                     p1 = __builtin_amdgcn_mfma_f32_32x32x16_bf16(kf[c & 1][2 * i + 1], qr[2 * c + i], p1, 0, 0, 0);
;                 }
;                 __builtin_amdgcn_sched_barrier(0);
;             }
;             if (more) ATT_GLOAD((FLAGS & AF_REV) ? t - 1 : t + 1);
;     ...
;             f32x2 rs2 = {0.f, 0.f};
; #pragma unroll
;             for (int r = 0; r < 16; ++r) { p0[r] = __builtin_amdgcn_exp2f(p0[r]); p1[r] = __builtin_amdgcn_exp2f(p1[r]); }
; #pragma unroll
;             for (int r = 0; r < 16; r += 2) { rs2 += (f32x2){p0[r], p0[r + 1]}; rs2 += (f32x2){p1[r], p1[r + 1]}; }
;             l += rs2.x + rs2.y;
;             bf16x8 pf[4];
;             pf[0] = pack_bf16x8(p0, 0); pf[1] = pack_bf16x8(p0, 8); pf[2] = pack_bf16x8(p1, 0); pf[3] = pack_bf16x8(p1, 8);
;             __builtin_amdgcn_sched_barrier(0);
; #pragma unroll
;             for (int d = 0; d < NDB; ++d) {
;                 if (d + 1 < NDB) {
; #pragma unroll
;                     for (int ks = 0; ks < 4; ++ks) vf[(d + 1) & 1][ks] = *(const LAS bf16x8*)(vb + (d + 1) * 32 * VROW + ks * 32);
;                 }
; #pragma unroll
;                 for (int ks = 0; ks < 4; ++ks) o[d] = __builtin_amdgcn_mfma_f32_32x32x16_bf16(vf[d & 1][ks], pf[ks], o[d], 0, 0, 0);
;                 __builtin_amdgcn_sched_barrier(0);
;             }
;         }
;         if (skip && more) ATT_GLOAD((FLAGS & AF_REV) ? t - 1 : t + 1);
;         if (more) ATT_LSTORE(cur ^ 1);
.Lq_top1:
	s_cmp_eq_u32 s3, 0
	s_cbranch_scc1 .Lq_gen1
	s_add_i32 s13, s3, 1
	s_cmp_ge_i32 s13, s20
	s_cbranch_scc1 .Lq_gen1
	ds_read_b128 v[96:99], v213 offset:0
	ds_read_b128 v[104:107], v213 offset:6656
	ds_read_b128 v[100:103], v213 offset:32
	ds_read_b128 v[108:111], v213 offset:6688
	ds_read_b128 v[112:115], v213 offset:64
	ds_read_b128 v[120:123], v213 offset:6720
	ds_read_b128 v[116:119], v213 offset:96
	ds_read_b128 v[124:127], v213 offset:6752
	v_mfma_f32_32x32x16_bf16 v[32:47], v[152:155], v[64:67], v[32:47]
	v_exp_f32_e32 v214, v214
	v_exp_f32_e32 v215, v215
	v_mfma_f32_32x32x16_bf16 v[16:31], v[188:191], v[64:67], v[16:31]
	v_exp_f32_e32 v230, v230
	v_exp_f32_e32 v231, v231
	v_add_f32_e32 v204, v214, v175
	s_waitcnt vmcnt(0)
	ds_write_b128 v248, v[140:143] offset:22528
	v_mfma_f32_32x32x16_bf16 v[32:47], v[156:159], v[68:71], v[32:47]
	v_exp_f32_e32 v216, v216
	v_exp_f32_e32 v217, v217
	v_add_f32_e32 v204, v230, v204
	v_add_f32_e32 v205, v215, v231
	ds_write_b128 v249, v[148:151] offset:35840
	v_mfma_f32_32x32x16_bf16 v[16:31], v[192:195], v[68:71], v[16:31]
	v_exp_f32_e32 v232, v232
	v_exp_f32_e32 v233, v233
	v_add_f32_e32 v204, v216, v204
	v_add_f32_e32 v205, v217, v205
	s_and_saveexec_b64 s[14:15], s[10:11]
	ds_write_b128 v250, v[144:147] offset:22528
	s_or_b64 exec, exec, s[14:15]
	v_mfma_f32_32x32x16_bf16 v[32:47], v[160:163], v[72:75], v[32:47]
	v_exp_f32_e32 v218, v218
	v_exp_f32_e32 v219, v219
	v_add_f32_e32 v204, v232, v204
	v_add_f32_e32 v205, v233, v205
	s_add_i32 s12, s3, 3
	s_cmp_ge_i32 s12, s2
	s_cbranch_scc1 .Lq_ng0_s1
	s_and_saveexec_b64 s[14:15], s[10:11]
	global_load_dwordx4 v[144:147], v180, s[98:99]
	s_or_b64 exec, exec, s[14:15]

; #define LAS __attribute__((address_space(3)))
; template <int DQK, int DV, int FLAGS, int qp, int kp, int vts, int op> ...
;     ...
;             for (int c = 0; c < ND0 / 2; ++c) {
;                 if (c + 1 < ND0 / 2) {
; #pragma unroll
;                     for (int i = 0; i < 2; ++i) { kf[(c + 1) & 1][2 * i] = *(const LAS bf16x8*)(kb + (2 * c + 2 + i) * 32); kf[(c + 1) & 1][2 * i + 1] = *(const LAS bf16x8*)(kb + 32 * KROW + (2 * c + 2 + i) * 32); }
;                 }
; #pragma unroll
;                 for (int i = 0; i < 2; ++i) {
;                     p0 = __builtin_amdgcn_mfma_f32_32x32x16_bf16(kf[c & 1][2 * i], qr[2 * c + i], p0, 0, 0, 0);
;                     p1 = __builtin_amdgcn_mfma_f32_32x32x16_bf16(kf[c & 1][2 * i + 1], qr[2 * c + i], p1, 0, 0, 0);
;                 }
;                 __builtin_amdgcn_sched_barrier(0);
;             }
;     ...
;             for (int r = 0; r < 16; ++r) { p0[r] = __builtin_amdgcn_exp2f(p0[r]); p1[r] = __builtin_amdgcn_exp2f(p1[r]); }
; #pragma unroll
;             for (int r = 0; r < 16; r += 2) { rs2 += (f32x2){p0[r], p0[r + 1]}; rs2 += (f32x2){p1[r], p1[r + 1]}; }
;             l += rs2.x + rs2.y;
;             bf16x8 pf[4];
;             pf[0] = pack_bf16x8(p0, 0); pf[1] = pack_bf16x8(p0, 8); pf[2] = pack_bf16x8(p1, 0); pf[3] = pack_bf16x8(p1, 8);
;             __builtin_amdgcn_sched_barrier(0);
; #pragma unroll
;             for (int d = 0; d < NDB; ++d) {
;                 if (d + 1 < NDB) {
; #pragma unroll
;                     for (int ks = 0; ks < 4; ++ks) vf[(d + 1) & 1][ks] = *(const LAS bf16x8*)(vb + (d + 1) * 32 * VROW + ks * 32);
;                 }
; #pragma unroll
;                 for (int ks = 0; ks < 4; ++ks) o[d] = __builtin_amdgcn_mfma_f32_32x32x16_bf16(vf[d & 1][ks], pf[ks], o[d], 0, 0, 0);
;                 __builtin_amdgcn_sched_barrier(0);
;             }
.Lq_ng2_s1:
	v_mfma_f32_32x32x16_bf16 v[16:31], v[200:203], v[76:79], v[16:31]
	v_exp_f32_e32 v236, v236
	v_exp_f32_e32 v237, v237
	v_add_f32_e32 v204, v220, v204
	v_add_f32_e32 v205, v221, v205
	ds_read_b128 v[152:155], v246 offset:35840
	ds_read_b128 v[156:159], v246 offset:35872
	ds_read_b128 v[160:163], v246 offset:35904
	ds_read_b128 v[164:167], v246 offset:35936
	s_waitcnt lgkmcnt(8)
	v_mfma_f32_32x32x16_bf16 v[64:79], v[96:99], v[2:5], v[48:63]
	v_exp_f32_e32 v222, v222
	v_exp_f32_e32 v223, v223
	v_add_f32_e32 v204, v236, v204
	v_add_f32_e32 v205, v237, v205
	v_mfma_f32_32x32x16_bf16 v[80:95], v[104:107], v[2:5], v[48:63]
	v_exp_f32_e32 v238, v238
	v_exp_f32_e32 v239, v239
	v_add_f32_e32 v204, v222, v204
	v_add_f32_e32 v205, v223, v205
	v_mfma_f32_32x32x16_bf16 v[64:79], v[100:103], v[6:9], v[64:79]
	v_exp_f32_e32 v224, v224
	v_exp_f32_e32 v225, v225
	v_add_f32_e32 v204, v238, v204
	v_add_f32_e32 v205, v239, v205
	v_mfma_f32_32x32x16_bf16 v[80:95], v[108:111], v[6:9], v[80:95]
	v_exp_f32_e32 v240, v240
	v_exp_f32_e32 v241, v241
	v_add_f32_e32 v204, v224, v204
	v_add_f32_e32 v205, v225, v205
	ds_read_b128 v[96:99], v213 offset:128
	ds_read_b128 v[104:107], v213 offset:6784
	ds_read_b128 v[100:103], v213 offset:160
	ds_read_b128 v[108:111], v213 offset:6816
	s_waitcnt lgkmcnt(8)
	v_mfma_f32_32x32x16_bf16 v[64:79], v[112:115], v[10:13], v[64:79]
	v_exp_f32_e32 v226, v226
	v_exp_f32_e32 v227, v227
	v_add_f32_e32 v204, v240, v204
	v_add_f32_e32 v205, v241, v205
	v_mfma_f32_32x32x16_bf16 v[80:95], v[120:123], v[10:13], v[80:95]
	v_exp_f32_e32 v242, v242
	v_exp_f32_e32 v243, v243
	v_add_f32_e32 v204, v226, v204
	v_add_f32_e32 v205, v227, v205
	v_mfma_f32_32x32x16_bf16 v[64:79], v[116:119], v[128:131], v[64:79]
	v_exp_f32_e32 v228, v228
	v_exp_f32_e32 v229, v229
	v_add_f32_e32 v204, v242, v204
	v_add_f32_e32 v205, v243, v205
	v_mfma_f32_32x32x16_bf16 v[80:95], v[124:127], v[128:131], v[80:95]
	v_exp_f32_e32 v244, v244
	v_exp_f32_e32 v245, v245
	v_add_f32_e32 v204, v228, v204
	v_add_f32_e32 v205, v229, v205
	ds_read_b128 v[188:191], v246 offset:40448
	ds_read_b128 v[192:195], v246 offset:40480
	ds_read_b128 v[196:199], v246 offset:40512
	ds_read_b128 v[200:203], v246 offset:40544
	s_waitcnt lgkmcnt(4)
	v_mfma_f32_32x32x16_bf16 v[64:79], v[96:99], v[132:135], v[64:79]
	s_nop 0
	v_add_f32_e32 v204, v244, v204
	v_add_f32_e32 v205, v245, v205
	v_cvt_pk_bf16_f32 v214, v214, v215
	v_cvt_pk_bf16_f32 v215, v216, v217
	v_cvt_pk_bf16_f32 v216, v218, v219
	v_mfma_f32_32x32x16_bf16 v[80:95], v[104:107], v[132:135], v[80:95]
	v_cvt_pk_bf16_f32 v217, v220, v221
	v_cvt_pk_bf16_f32 v218, v222, v223
	v_cvt_pk_bf16_f32 v219, v224, v225
	v_cvt_pk_bf16_f32 v220, v226, v227
	v_cvt_pk_bf16_f32 v221, v228, v229
	v_mfma_f32_32x32x16_bf16 v[64:79], v[100:103], v[136:139], v[64:79]
	v_cvt_pk_bf16_f32 v222, v230, v231
	v_cvt_pk_bf16_f32 v223, v232, v233
	v_cvt_pk_bf16_f32 v224, v234, v235
	v_cvt_pk_bf16_f32 v225, v236, v237
	v_cvt_pk_bf16_f32 v226, v238, v239
	v_mfma_f32_32x32x16_bf16 v[80:95], v[108:111], v[136:139], v[80:95]
	v_cvt_pk_bf16_f32 v227, v240, v241
	v_cvt_pk_bf16_f32 v228, v242, v243
	v_cvt_pk_bf16_f32 v229, v244, v245
	v_add_f32_e32 v175, v204, v205
	s_branch .Lq_tailb1

; template <int DQK, int DV, int FLAGS, int qp, int kp, int vts, int op> ...
;     ...
;             f32x2 rs2 = {0.f, 0.f};
; #pragma unroll
;             for (int r = 0; r < 16; ++r) { p0[r] = __builtin_amdgcn_exp2f(p0[r]); p1[r] = __builtin_amdgcn_exp2f(p1[r]); }
; #pragma unroll
;             for (int r = 0; r < 16; r += 2) { rs2 += (f32x2){p0[r], p0[r + 1]}; rs2 += (f32x2){p1[r], p1[r + 1]}; }
;             l += rs2.x + rs2.y;
;             bf16x8 pf[4];
;             pf[0] = pack_bf16x8(p0, 0); pf[1] = pack_bf16x8(p0, 8); pf[2] = pack_bf16x8(p1, 0); pf[3] = pack_bf16x8(p1, 8);
.Lq_notfirst_q1:
	v_exp_f32_e32 v214, v214
	v_exp_f32_e32 v215, v215
	v_exp_f32_e32 v230, v230
	v_exp_f32_e32 v231, v231
	v_add_f32_e32 v204, v214, v175
	v_exp_f32_e32 v216, v216
	v_exp_f32_e32 v217, v217
	v_add_f32_e32 v204, v230, v204
	v_add_f32_e32 v205, v215, v231
	v_exp_f32_e32 v232, v232
	v_exp_f32_e32 v233, v233
	v_add_f32_e32 v204, v216, v204
	v_add_f32_e32 v205, v217, v205
	v_exp_f32_e32 v218, v218
	v_exp_f32_e32 v219, v219
	v_add_f32_e32 v204, v232, v204
	v_add_f32_e32 v205, v233, v205
	v_exp_f32_e32 v234, v234
	v_exp_f32_e32 v235, v235
	v_add_f32_e32 v204, v218, v204
	v_add_f32_e32 v205, v219, v205
	v_exp_f32_e32 v220, v220
	v_exp_f32_e32 v221, v221
	v_add_f32_e32 v204, v234, v204
	v_add_f32_e32 v205, v235, v205
	v_exp_f32_e32 v236, v236
	v_exp_f32_e32 v237, v237
	v_add_f32_e32 v204, v220, v204
	v_add_f32_e32 v205, v221, v205
	v_exp_f32_e32 v222, v222
	v_exp_f32_e32 v223, v223
	v_add_f32_e32 v204, v236, v204
	v_add_f32_e32 v205, v237, v205
	v_exp_f32_e32 v238, v238
	v_exp_f32_e32 v239, v239
	v_add_f32_e32 v204, v222, v204
	v_add_f32_e32 v205, v223, v205
	v_exp_f32_e32 v224, v224
	v_exp_f32_e32 v225, v225
	v_add_f32_e32 v204, v238, v204
	v_add_f32_e32 v205, v239, v205
	v_exp_f32_e32 v240, v240
	v_exp_f32_e32 v241, v241
	v_add_f32_e32 v204, v224, v204
	v_add_f32_e32 v205, v225, v205
	v_exp_f32_e32 v226, v226
	v_exp_f32_e32 v227, v227
	v_add_f32_e32 v204, v240, v204
	v_add_f32_e32 v205, v241, v205
	v_exp_f32_e32 v242, v242
	v_exp_f32_e32 v243, v243
	v_add_f32_e32 v204, v226, v204
	v_add_f32_e32 v205, v227, v205
	v_exp_f32_e32 v228, v228
	v_exp_f32_e32 v229, v229
	v_add_f32_e32 v204, v242, v204
	v_add_f32_e32 v205, v243, v205
	v_exp_f32_e32 v244, v244
	v_exp_f32_e32 v245, v245
	v_add_f32_e32 v204, v228, v204
	v_add_f32_e32 v205, v229, v205
	s_nop 0
	v_add_f32_e32 v204, v244, v204
	v_add_f32_e32 v205, v245, v205
	v_cvt_pk_bf16_f32 v214, v214, v215
	v_cvt_pk_bf16_f32 v215, v216, v217
	v_cvt_pk_bf16_f32 v216, v218, v219
	v_cvt_pk_bf16_f32 v217, v220, v221
	v_cvt_pk_bf16_f32 v218, v222, v223
	v_cvt_pk_bf16_f32 v219, v224, v225
	v_cvt_pk_bf16_f32 v220, v226, v227
	v_cvt_pk_bf16_f32 v221, v228, v229
	v_cvt_pk_bf16_f32 v222, v230, v231
	v_cvt_pk_bf16_f32 v223, v232, v233
	v_cvt_pk_bf16_f32 v224, v234, v235
	v_cvt_pk_bf16_f32 v225, v236, v237
	v_cvt_pk_bf16_f32 v226, v238, v239
	v_cvt_pk_bf16_f32 v227, v240, v241
	v_cvt_pk_bf16_f32 v228, v242, v243
	v_cvt_pk_bf16_f32 v229, v244, v245
	v_add_f32_e32 v175, v204, v205

; #define LAS __attribute__((address_space(3)))
; template <int DQK, int DV, int FLAGS, int qp, int kp, int vts, int op> ...
;     ...
;             for (int c = 0; c < ND0 / 2; ++c) {
;                 if (c + 1 < ND0 / 2) {
; #pragma unroll
;                     for (int i = 0; i < 2; ++i) { kf[(c + 1) & 1][2 * i] = *(const LAS bf16x8*)(kb + (2 * c + 2 + i) * 32); kf[(c + 1) & 1][2 * i + 1] = *(const LAS bf16x8*)(kb + 32 * KROW + (2 * c + 2 + i) * 32); }
;                 }
; #pragma unroll
;                 for (int i = 0; i < 2; ++i) {
;                     p0 = __builtin_amdgcn_mfma_f32_32x32x16_bf16(kf[c & 1][2 * i], qr[2 * c + i], p0, 0, 0, 0);
;                     p1 = __builtin_amdgcn_mfma_f32_32x32x16_bf16(kf[c & 1][2 * i + 1], qr[2 * c + i], p1, 0, 0, 0);
;                 }
;                 __builtin_amdgcn_sched_barrier(0);
;             }
;             if (more) ATT_GLOAD((FLAGS & AF_REV) ? t - 1 : t + 1);
;     ...
;             f32x2 rs2 = {0.f, 0.f};
; #pragma unroll
;             for (int r = 0; r < 16; ++r) { p0[r] = __builtin_amdgcn_exp2f(p0[r]); p1[r] = __builtin_amdgcn_exp2f(p1[r]); }
; #pragma unroll
;             for (int r = 0; r < 16; r += 2) { rs2 += (f32x2){p0[r], p0[r + 1]}; rs2 += (f32x2){p1[r], p1[r + 1]}; }
;             l += rs2.x + rs2.y;
;             bf16x8 pf[4];
;             pf[0] = pack_bf16x8(p0, 0); pf[1] = pack_bf16x8(p0, 8); pf[2] = pack_bf16x8(p1, 0); pf[3] = pack_bf16x8(p1, 8);
;             __builtin_amdgcn_sched_barrier(0);
; #pragma unroll
;             for (int d = 0; d < NDB; ++d) {
;                 if (d + 1 < NDB) {
; #pragma unroll
;                     for (int ks = 0; ks < 4; ++ks) vf[(d + 1) & 1][ks] = *(const LAS bf16x8*)(vb + (d + 1) * 32 * VROW + ks * 32);
;                 }
; #pragma unroll
;                 for (int ks = 0; ks < 4; ++ks) o[d] = __builtin_amdgcn_mfma_f32_32x32x16_bf16(vf[d & 1][ks], pf[ks], o[d], 0, 0, 0);
;                 __builtin_amdgcn_sched_barrier(0);
;             }
;         }
;         if (skip && more) ATT_GLOAD((FLAGS & AF_REV) ? t - 1 : t + 1);
;         if (more) ATT_LSTORE(cur ^ 1);
.Lq_top2:
	s_cmp_eq_u32 s3, 0
	s_cbranch_scc1 .Lq_gen2
	s_add_i32 s13, s3, 1
	s_cmp_ge_i32 s13, s20
	s_cbranch_scc1 .Lq_gen2
	ds_read_b128 v[96:99], v213 offset:22528
	ds_read_b128 v[104:107], v213 offset:29184
	ds_read_b128 v[100:103], v213 offset:22560
	ds_read_b128 v[108:111], v213 offset:29216
	ds_read_b128 v[112:115], v213 offset:22592
	ds_read_b128 v[120:123], v213 offset:29248
	ds_read_b128 v[116:119], v213 offset:22624
	ds_read_b128 v[124:127], v213 offset:29280
	v_mfma_f32_32x32x16_bf16 v[32:47], v[152:155], v[214:217], v[32:47]
	v_exp_f32_e32 v64, v64
	v_exp_f32_e32 v65, v65
	v_mfma_f32_32x32x16_bf16 v[16:31], v[188:191], v[214:217], v[16:31]
	v_exp_f32_e32 v80, v80
	v_exp_f32_e32 v81, v81
	v_add_f32_e32 v204, v64, v175
	s_waitcnt vmcnt(0)
	ds_write_b128 v14, v[140:143] offset:0
	v_mfma_f32_32x32x16_bf16 v[32:47], v[156:159], v[218:221], v[32:47]
	v_exp_f32_e32 v66, v66
	v_exp_f32_e32 v67, v67
	v_add_f32_e32 v204, v80, v204
	v_add_f32_e32 v205, v65, v81
	ds_write_b128 v174, v[148:151] offset:13312
	v_mfma_f32_32x32x16_bf16 v[16:31], v[192:195], v[218:221], v[16:31]
	v_exp_f32_e32 v82, v82
	v_exp_f32_e32 v83, v83
	v_add_f32_e32 v204, v66, v204
	v_add_f32_e32 v205, v67, v205
	s_and_saveexec_b64 s[14:15], s[10:11]
	ds_write_b128 v172, v[144:147] offset:0
	s_or_b64 exec, exec, s[14:15]
	v_mfma_f32_32x32x16_bf16 v[32:47], v[160:163], v[222:225], v[32:47]
	v_exp_f32_e32 v68, v68
	v_exp_f32_e32 v69, v69
	v_add_f32_e32 v204, v82, v204
	v_add_f32_e32 v205, v83, v205
	s_add_i32 s12, s3, 3
	s_cmp_ge_i32 s12, s2
	s_cbranch_scc1 .Lq_ng0_s2
	s_and_saveexec_b64 s[14:15], s[10:11]
	global_load_dwordx4 v[144:147], v180, s[98:99]
	s_or_b64 exec, exec, s[14:15]

; #define LAS __attribute__((address_space(3)))
; template <int DQK, int DV, int FLAGS, int qp, int kp, int vts, int op> ...
;     ...
;             for (int c = 0; c < ND0 / 2; ++c) {
;                 if (c + 1 < ND0 / 2) {
; #pragma unroll
;                     for (int i = 0; i < 2; ++i) { kf[(c + 1) & 1][2 * i] = *(const LAS bf16x8*)(kb + (2 * c + 2 + i) * 32); kf[(c + 1) & 1][2 * i + 1] = *(const LAS bf16x8*)(kb + 32 * KROW + (2 * c + 2 + i) * 32); }
;                 }
; #pragma unroll
;                 for (int i = 0; i < 2; ++i) {
;                     p0 = __builtin_amdgcn_mfma_f32_32x32x16_bf16(kf[c & 1][2 * i], qr[2 * c + i], p0, 0, 0, 0);
;                     p1 = __builtin_amdgcn_mfma_f32_32x32x16_bf16(kf[c & 1][2 * i + 1], qr[2 * c + i], p1, 0, 0, 0);
;                 }
;                 __builtin_amdgcn_sched_barrier(0);
;             }
;     ...
;             for (int r = 0; r < 16; ++r) { p0[r] = __builtin_amdgcn_exp2f(p0[r]); p1[r] = __builtin_amdgcn_exp2f(p1[r]); }
; #pragma unroll
;             for (int r = 0; r < 16; r += 2) { rs2 += (f32x2){p0[r], p0[r + 1]}; rs2 += (f32x2){p1[r], p1[r + 1]}; }
;             l += rs2.x + rs2.y;
;             bf16x8 pf[4];
;             pf[0] = pack_bf16x8(p0, 0); pf[1] = pack_bf16x8(p0, 8); pf[2] = pack_bf16x8(p1, 0); pf[3] = pack_bf16x8(p1, 8);
;             __builtin_amdgcn_sched_barrier(0);
; #pragma unroll
;             for (int d = 0; d < NDB; ++d) {
;                 if (d + 1 < NDB) {
; #pragma unroll
;                     for (int ks = 0; ks < 4; ++ks) vf[(d + 1) & 1][ks] = *(const LAS bf16x8*)(vb + (d + 1) * 32 * VROW + ks * 32);
;                 }
; #pragma unroll
;                 for (int ks = 0; ks < 4; ++ks) o[d] = __builtin_amdgcn_mfma_f32_32x32x16_bf16(vf[d & 1][ks], pf[ks], o[d], 0, 0, 0);
;                 __builtin_amdgcn_sched_barrier(0);
;             }
.Lq_ng2_s2:
	v_mfma_f32_32x32x16_bf16 v[16:31], v[200:203], v[226:229], v[16:31]
	v_exp_f32_e32 v86, v86
	v_exp_f32_e32 v87, v87
	v_add_f32_e32 v204, v70, v204
	v_add_f32_e32 v205, v71, v205
	ds_read_b128 v[152:155], v247 offset:13312
	ds_read_b128 v[156:159], v247 offset:13344
	ds_read_b128 v[160:163], v247 offset:13376
	ds_read_b128 v[164:167], v247 offset:13408
	s_waitcnt lgkmcnt(8)
	v_mfma_f32_32x32x16_bf16 v[214:229], v[96:99], v[2:5], v[48:63]
	v_exp_f32_e32 v72, v72
	v_exp_f32_e32 v73, v73
	v_add_f32_e32 v204, v86, v204
	v_add_f32_e32 v205, v87, v205
	v_mfma_f32_32x32x16_bf16 v[230:245], v[104:107], v[2:5], v[48:63]
	v_exp_f32_e32 v88, v88
	v_exp_f32_e32 v89, v89
	v_add_f32_e32 v204, v72, v204
	v_add_f32_e32 v205, v73, v205
	v_mfma_f32_32x32x16_bf16 v[214:229], v[100:103], v[6:9], v[214:229]
	v_exp_f32_e32 v74, v74
	v_exp_f32_e32 v75, v75
	v_add_f32_e32 v204, v88, v204
	v_add_f32_e32 v205, v89, v205
	v_mfma_f32_32x32x16_bf16 v[230:245], v[108:111], v[6:9], v[230:245]
	v_exp_f32_e32 v90, v90
	v_exp_f32_e32 v91, v91
	v_add_f32_e32 v204, v74, v204
	v_add_f32_e32 v205, v75, v205
	ds_read_b128 v[96:99], v213 offset:22656
	ds_read_b128 v[104:107], v213 offset:29312
	ds_read_b128 v[100:103], v213 offset:22688
	ds_read_b128 v[108:111], v213 offset:29344
	s_waitcnt lgkmcnt(8)
	v_mfma_f32_32x32x16_bf16 v[214:229], v[112:115], v[10:13], v[214:229]
	v_exp_f32_e32 v76, v76
	v_exp_f32_e32 v77, v77
	v_add_f32_e32 v204, v90, v204
	v_add_f32_e32 v205, v91, v205
	v_mfma_f32_32x32x16_bf16 v[230:245], v[120:123], v[10:13], v[230:245]
	v_exp_f32_e32 v92, v92
	v_exp_f32_e32 v93, v93
	v_add_f32_e32 v204, v76, v204
	v_add_f32_e32 v205, v77, v205
	v_mfma_f32_32x32x16_bf16 v[214:229], v[116:119], v[128:131], v[214:229]
	v_exp_f32_e32 v78, v78
	v_exp_f32_e32 v79, v79
	v_add_f32_e32 v204, v92, v204
	v_add_f32_e32 v205, v93, v205
	v_mfma_f32_32x32x16_bf16 v[230:245], v[124:127], v[128:131], v[230:245]
	v_exp_f32_e32 v94, v94
	v_exp_f32_e32 v95, v95
	v_add_f32_e32 v204, v78, v204
	v_add_f32_e32 v205, v79, v205
	ds_read_b128 v[188:191], v247 offset:17920
	ds_read_b128 v[192:195], v247 offset:17952
	ds_read_b128 v[196:199], v247 offset:17984
	ds_read_b128 v[200:203], v247 offset:18016
	s_waitcnt lgkmcnt(4)
	v_mfma_f32_32x32x16_bf16 v[214:229], v[96:99], v[132:135], v[214:229]
	s_nop 0
	v_add_f32_e32 v204, v94, v204
	v_add_f32_e32 v205, v95, v205
	v_cvt_pk_bf16_f32 v64, v64, v65
	v_cvt_pk_bf16_f32 v65, v66, v67
	v_cvt_pk_bf16_f32 v66, v68, v69
	v_mfma_f32_32x32x16_bf16 v[230:245], v[104:107], v[132:135], v[230:245]
	v_cvt_pk_bf16_f32 v67, v70, v71
	v_cvt_pk_bf16_f32 v68, v72, v73
	v_cvt_pk_bf16_f32 v69, v74, v75
	v_cvt_pk_bf16_f32 v70, v76, v77
	v_cvt_pk_bf16_f32 v71, v78, v79
	v_mfma_f32_32x32x16_bf16 v[214:229], v[100:103], v[136:139], v[214:229]
	v_cvt_pk_bf16_f32 v72, v80, v81
	v_cvt_pk_bf16_f32 v73, v82, v83
	v_cvt_pk_bf16_f32 v74, v84, v85
	v_cvt_pk_bf16_f32 v75, v86, v87
	v_cvt_pk_bf16_f32 v76, v88, v89
	v_mfma_f32_32x32x16_bf16 v[230:245], v[108:111], v[136:139], v[230:245]
	v_cvt_pk_bf16_f32 v77, v90, v91
	v_cvt_pk_bf16_f32 v78, v92, v93
	v_cvt_pk_bf16_f32 v79, v94, v95
	v_add_f32_e32 v175, v204, v205
	s_branch .Lq_tailb2

; #define LAS __attribute__((address_space(3)))
; template <int DQK, int DV, int FLAGS, int qp, int kp, int vts, int op> ...
;     ...
;             for (int c = 0; c < ND0 / 2; ++c) {
;                 if (c + 1 < ND0 / 2) {
; #pragma unroll
;                     for (int i = 0; i < 2; ++i) { kf[(c + 1) & 1][2 * i] = *(const LAS bf16x8*)(kb + (2 * c + 2 + i) * 32); kf[(c + 1) & 1][2 * i + 1] = *(const LAS bf16x8*)(kb + 32 * KROW + (2 * c + 2 + i) * 32); }
;                 }
; #pragma unroll
;                 for (int i = 0; i < 2; ++i) {
;                     p0 = __builtin_amdgcn_mfma_f32_32x32x16_bf16(kf[c & 1][2 * i], qr[2 * c + i], p0, 0, 0, 0);
;                     p1 = __builtin_amdgcn_mfma_f32_32x32x16_bf16(kf[c & 1][2 * i + 1], qr[2 * c + i], p1, 0, 0, 0);
;                 }
;                 __builtin_amdgcn_sched_barrier(0);
;             }
;             if (more) ATT_GLOAD((FLAGS & AF_REV) ? t - 1 : t + 1);
;     ...
;             f32x2 rs2 = {0.f, 0.f};
; #pragma unroll
;             for (int r = 0; r < 16; ++r) { p0[r] = __builtin_amdgcn_exp2f(p0[r]); p1[r] = __builtin_amdgcn_exp2f(p1[r]); }
; #pragma unroll
;             for (int r = 0; r < 16; r += 2) { rs2 += (f32x2){p0[r], p0[r + 1]}; rs2 += (f32x2){p1[r], p1[r + 1]}; }
;             l += rs2.x + rs2.y;
;             bf16x8 pf[4];
;             pf[0] = pack_bf16x8(p0, 0); pf[1] = pack_bf16x8(p0, 8); pf[2] = pack_bf16x8(p1, 0); pf[3] = pack_bf16x8(p1, 8);
;             __builtin_amdgcn_sched_barrier(0);
; #pragma unroll
;             for (int d = 0; d < NDB; ++d) {
;                 if (d + 1 < NDB) {
; #pragma unroll
;                     for (int ks = 0; ks < 4; ++ks) vf[(d + 1) & 1][ks] = *(const LAS bf16x8*)(vb + (d + 1) * 32 * VROW + ks * 32);
;                 }
; #pragma unroll
;                 for (int ks = 0; ks < 4; ++ks) o[d] = __builtin_amdgcn_mfma_f32_32x32x16_bf16(vf[d & 1][ks], pf[ks], o[d], 0, 0, 0);
;                 __builtin_amdgcn_sched_barrier(0);
;             }
;         }
;         if (skip && more) ATT_GLOAD((FLAGS & AF_REV) ? t - 1 : t + 1);
;         if (more) ATT_LSTORE(cur ^ 1);
.Lq_top3:
	s_cmp_eq_u32 s3, 0
	s_cbranch_scc1 .Lq_gen3
	s_add_i32 s13, s3, 1
	s_cmp_ge_i32 s13, s20
	s_cbranch_scc1 .Lq_gen3
	ds_read_b128 v[96:99], v187 offset:0
	ds_read_b128 v[104:107], v187 offset:6656
	ds_read_b128 v[100:103], v187 offset:32
	ds_read_b128 v[108:111], v187 offset:6688
	ds_read_b128 v[112:115], v187 offset:64
	ds_read_b128 v[120:123], v187 offset:6720
	ds_read_b128 v[116:119], v187 offset:96
	ds_read_b128 v[124:127], v187 offset:6752
	v_mfma_f32_32x32x16_bf16 v[32:47], v[152:155], v[64:67], v[32:47]
	v_exp_f32_e32 v214, v214
	v_exp_f32_e32 v215, v215
	v_mfma_f32_32x32x16_bf16 v[16:31], v[188:191], v[64:67], v[16:31]
	v_exp_f32_e32 v230, v230
	v_exp_f32_e32 v231, v231
	v_add_f32_e32 v204, v214, v175
	s_waitcnt vmcnt(0)
	ds_write_b128 v14, v[140:143] offset:22528
	v_mfma_f32_32x32x16_bf16 v[32:47], v[156:159], v[68:71], v[32:47]
	v_exp_f32_e32 v216, v216
	v_exp_f32_e32 v217, v217
	v_add_f32_e32 v204, v230, v204
	v_add_f32_e32 v205, v215, v231
	ds_write_b128 v174, v[148:151] offset:35840
	v_mfma_f32_32x32x16_bf16 v[16:31], v[192:195], v[68:71], v[16:31]
	v_exp_f32_e32 v232, v232
	v_exp_f32_e32 v233, v233
	v_add_f32_e32 v204, v216, v204
	v_add_f32_e32 v205, v217, v205
	s_and_saveexec_b64 s[14:15], s[10:11]
	ds_write_b128 v172, v[144:147] offset:22528
	s_or_b64 exec, exec, s[14:15]
	v_mfma_f32_32x32x16_bf16 v[32:47], v[160:163], v[72:75], v[32:47]
	v_exp_f32_e32 v218, v218
	v_exp_f32_e32 v219, v219
	v_add_f32_e32 v204, v232, v204
	v_add_f32_e32 v205, v233, v205
	s_add_i32 s12, s3, 3
	s_cmp_ge_i32 s12, s2
	s_cbranch_scc1 .Lq_ng0_s3
	s_and_saveexec_b64 s[14:15], s[10:11]
	global_load_dwordx4 v[144:147], v180, s[98:99]
	s_or_b64 exec, exec, s[14:15]

; #define LAS __attribute__((address_space(3)))
; template <int DQK, int DV, int FLAGS, int qp, int kp, int vts, int op> ...
;     ...
;             for (int c = 0; c < ND0 / 2; ++c) {
;                 if (c + 1 < ND0 / 2) {
; #pragma unroll
;                     for (int i = 0; i < 2; ++i) { kf[(c + 1) & 1][2 * i] = *(const LAS bf16x8*)(kb + (2 * c + 2 + i) * 32); kf[(c + 1) & 1][2 * i + 1] = *(const LAS bf16x8*)(kb + 32 * KROW + (2 * c + 2 + i) * 32); }
;                 }
; #pragma unroll
;                 for (int i = 0; i < 2; ++i) {
;                     p0 = __builtin_amdgcn_mfma_f32_32x32x16_bf16(kf[c & 1][2 * i], qr[2 * c + i], p0, 0, 0, 0);
;                     p1 = __builtin_amdgcn_mfma_f32_32x32x16_bf16(kf[c & 1][2 * i + 1], qr[2 * c + i], p1, 0, 0, 0);
;                 }
;                 __builtin_amdgcn_sched_barrier(0);
;             }
;     ...
;             for (int r = 0; r < 16; ++r) { p0[r] = __builtin_amdgcn_exp2f(p0[r]); p1[r] = __builtin_amdgcn_exp2f(p1[r]); }
; #pragma unroll
;             for (int r = 0; r < 16; r += 2) { rs2 += (f32x2){p0[r], p0[r + 1]}; rs2 += (f32x2){p1[r], p1[r + 1]}; }
;             l += rs2.x + rs2.y;
;             bf16x8 pf[4];
;             pf[0] = pack_bf16x8(p0, 0); pf[1] = pack_bf16x8(p0, 8); pf[2] = pack_bf16x8(p1, 0); pf[3] = pack_bf16x8(p1, 8);
;             __builtin_amdgcn_sched_barrier(0);
; #pragma unroll
;             for (int d = 0; d < NDB; ++d) {
;                 if (d + 1 < NDB) {
; #pragma unroll
;                     for (int ks = 0; ks < 4; ++ks) vf[(d + 1) & 1][ks] = *(const LAS bf16x8*)(vb + (d + 1) * 32 * VROW + ks * 32);
;                 }
; #pragma unroll
;                 for (int ks = 0; ks < 4; ++ks) o[d] = __builtin_amdgcn_mfma_f32_32x32x16_bf16(vf[d & 1][ks], pf[ks], o[d], 0, 0, 0);
;                 __builtin_amdgcn_sched_barrier(0);
;             }
.Lq_ng2_s3:
	v_mfma_f32_32x32x16_bf16 v[16:31], v[200:203], v[76:79], v[16:31]
	v_exp_f32_e32 v236, v236
	v_exp_f32_e32 v237, v237
	v_add_f32_e32 v204, v220, v204
	v_add_f32_e32 v205, v221, v205
	ds_read_b128 v[152:155], v247 offset:35840
	ds_read_b128 v[156:159], v247 offset:35872
	ds_read_b128 v[160:163], v247 offset:35904
	ds_read_b128 v[164:167], v247 offset:35936
	s_waitcnt lgkmcnt(8)
	v_mfma_f32_32x32x16_bf16 v[64:79], v[96:99], v[2:5], v[48:63]
	v_exp_f32_e32 v222, v222
	v_exp_f32_e32 v223, v223
	v_add_f32_e32 v204, v236, v204
	v_add_f32_e32 v205, v237, v205
	v_mfma_f32_32x32x16_bf16 v[80:95], v[104:107], v[2:5], v[48:63]
	v_exp_f32_e32 v238, v238
	v_exp_f32_e32 v239, v239
	v_add_f32_e32 v204, v222, v204
	v_add_f32_e32 v205, v223, v205
	v_mfma_f32_32x32x16_bf16 v[64:79], v[100:103], v[6:9], v[64:79]
	v_exp_f32_e32 v224, v224
	v_exp_f32_e32 v225, v225
	v_add_f32_e32 v204, v238, v204
	v_add_f32_e32 v205, v239, v205
	v_mfma_f32_32x32x16_bf16 v[80:95], v[108:111], v[6:9], v[80:95]
	v_exp_f32_e32 v240, v240
	v_exp_f32_e32 v241, v241
	v_add_f32_e32 v204, v224, v204
	v_add_f32_e32 v205, v225, v205
	ds_read_b128 v[96:99], v187 offset:128
	ds_read_b128 v[104:107], v187 offset:6784
	ds_read_b128 v[100:103], v187 offset:160
	ds_read_b128 v[108:111], v187 offset:6816
	s_waitcnt lgkmcnt(8)
	v_mfma_f32_32x32x16_bf16 v[64:79], v[112:115], v[10:13], v[64:79]
	v_exp_f32_e32 v226, v226
	v_exp_f32_e32 v227, v227
	v_add_f32_e32 v204, v240, v204
	v_add_f32_e32 v205, v241, v205
	v_mfma_f32_32x32x16_bf16 v[80:95], v[120:123], v[10:13], v[80:95]
	v_exp_f32_e32 v242, v242
	v_exp_f32_e32 v243, v243
	v_add_f32_e32 v204, v226, v204
	v_add_f32_e32 v205, v227, v205
	v_mfma_f32_32x32x16_bf16 v[64:79], v[116:119], v[128:131], v[64:79]
	v_exp_f32_e32 v228, v228
	v_exp_f32_e32 v229, v229
	v_add_f32_e32 v204, v242, v204
	v_add_f32_e32 v205, v243, v205
	v_mfma_f32_32x32x16_bf16 v[80:95], v[124:127], v[128:131], v[80:95]
	v_exp_f32_e32 v244, v244
	v_exp_f32_e32 v245, v245
	v_add_f32_e32 v204, v228, v204
	v_add_f32_e32 v205, v229, v205
	ds_read_b128 v[188:191], v247 offset:40448
	ds_read_b128 v[192:195], v247 offset:40480
	ds_read_b128 v[196:199], v247 offset:40512
	ds_read_b128 v[200:203], v247 offset:40544
	s_waitcnt lgkmcnt(4)
	v_mfma_f32_32x32x16_bf16 v[64:79], v[96:99], v[132:135], v[64:79]
	s_nop 0
	v_add_f32_e32 v204, v244, v204
	v_add_f32_e32 v205, v245, v205
	v_cvt_pk_bf16_f32 v214, v214, v215
	v_cvt_pk_bf16_f32 v215, v216, v217
	v_cvt_pk_bf16_f32 v216, v218, v219
	v_mfma_f32_32x32x16_bf16 v[80:95], v[104:107], v[132:135], v[80:95]
	v_cvt_pk_bf16_f32 v217, v220, v221
	v_cvt_pk_bf16_f32 v218, v222, v223
	v_cvt_pk_bf16_f32 v219, v224, v225
	v_cvt_pk_bf16_f32 v220, v226, v227
	v_cvt_pk_bf16_f32 v221, v228, v229
	v_mfma_f32_32x32x16_bf16 v[64:79], v[100:103], v[136:139], v[64:79]
	v_cvt_pk_bf16_f32 v222, v230, v231
	v_cvt_pk_bf16_f32 v223, v232, v233
	v_cvt_pk_bf16_f32 v224, v234, v235
	v_cvt_pk_bf16_f32 v225, v236, v237
	v_cvt_pk_bf16_f32 v226, v238, v239
	v_mfma_f32_32x32x16_bf16 v[80:95], v[108:111], v[136:139], v[80:95]
	v_cvt_pk_bf16_f32 v227, v240, v241
	v_cvt_pk_bf16_f32 v228, v242, v243
	v_cvt_pk_bf16_f32 v229, v244, v245
	v_add_f32_e32 v175, v204, v205
	s_branch .Lq_tailb3

; template <int DQK, int DV, int FLAGS, int qp, int kp, int vts, int op> ...
;     ...
;     u32x4 kreg[KPT], vreg[VPT];
;     unsigned kgo[KPT], vgo[VPT], klo[KPT], vlo[VPT];
; #pragma unroll
;     for (int i = 0; i < KPT; ++i) { const int c = tid + i * NTHREADS; const int row = c / KC, cc = c % KC; kgo[i] = (unsigned)(row * kp + cc * 8) * 2u; klo[i] = (unsigned)(row * KROW + cc * 16); }
; #pragma unroll
;     for (int i = 0; i < VPT; ++i) { const int c = tid + i * NTHREADS; const int d = c >> 3, cc = c & 7; vgo[i] = (unsigned)(d * vts + cc * 8) * 2u; vlo[i] = (unsigned)(KT_BYTES + d * VROW + cc * 16); }
;     ...
;     ATT_GLOAD((FLAGS & AF_REV) ? kt_hi - 1 : kt_lo); ATT_LSTORE(0);
;     __syncthreads();
;     bool started = false;
;     const int prow = (r32 & ~12) | ((r32 & 4) << 1) | ((r32 & 8) >> 1);
;     const int ntile = kt_hi - kt_lo;
;     for (int it = 0; it < ntile; ++it) {
;         const int t = (FLAGS & AF_REV) ? kt_hi - 1 - it : kt_lo + it;
;         const int cur = it & 1;
;         const bool more = (it + 1 < ntile);
;         const int kv0 = t * 64;
;         bool skip = false;
;         if (FLAGS & AF_CAUSAL) skip = skip || (kv0 > qmax_w);
;         if (FLAGS & AF_WINDOW) skip = skip || (kv0 + 63 < qmin_w - (SWA_W - 1));
;         if (!skip) {
;             const LAS unsigned char* kb = lds + cur * BUF + prow * KROW + 16 * hi;
;             const LAS unsigned char* vb = lds + cur * BUF + KT_BYTES + r32 * VROW + 16 * hi;
;             f32x16 p0, p1;
;             bf16x8 kf[2][4];
; #pragma unroll
;             for (int i = 0; i < 2; ++i) { kf[0][2 * i] = *(const LAS bf16x8*)(kb + i * 32); kf[0][2 * i + 1] = *(const LAS bf16x8*)(kb + 32 * KROW + i * 32); }
;             const int nrel = qpos - kv0 - 8 * hi;
;             if (FLAGS & AF_ALIBI) { const float ab = -slope2 * (float)nrel - ((FLAGS & AF_ROBUST) ? 0.f : m);
; #pragma unroll
;                 for (int r = 0; r < 16; ++r) { const float c = (float)(16 * (r >> 3) + (r & 7)); p0[r] = __builtin_fmaf(slope2, c, ab); p1[r] = __builtin_fmaf(slope2, c + 32.f, ab); }
;             } else if (FLAGS & AF_ROBUST) {
; #pragma unroll
;                 for (int r = 0; r < 16; ++r) { p0[r] = 0.f; p1[r] = 0.f; }
;             } else { p0 = negm; p1 = negm; }
;             __builtin_amdgcn_sched_barrier(0);
; #pragma unroll
;             for (int c = 0; c < ND0 / 2; ++c) {
;                 if (c + 1 < ND0 / 2) {
.LBB0_933:
	s_andn2_b64 vcc, exec, s[8:9]
	v_lshlrev_b32_e32 v198, 3, v17
	s_cbranch_vccnz .LBB0_923
	v_and_b32_e32 v18, 31, v15
	v_and_b32_e32 v19, 19, v15
	v_lshlrev_b32_e32 v20, 1, v15
	v_lshrrev_b32_e32 v15, 1, v15
	s_and_b32 s8, s2, 0xffffffe0
	v_readlane_b32 s12, v255, 39
	v_and_b32_e32 v20, 8, v20
	v_and_b32_e32 v15, 4, v15
	v_mov_b32_e32 v17, v1
	s_add_i32 s20, s8, s12
	v_or3_b32 v15, v19, v20, v15
	s_addk_i32 s8, 0xff40
	v_mov_b32_e32 v64, v1
	v_mov_b32_e32 v65, v1
	v_mul_u32_u24_e32 v201, 0x90, v15
	v_mul_u32_u24_e32 v203, 0x90, v18
	v_lshl_add_u64 v[206:207], s[6:7], 0, v[16:17]
	v_add_u32_e32 v15, s8, v18
	v_mov_b32_e32 v66, v1
	v_mov_b32_e32 v67, v1
	v_mov_b32_e32 v68, v1
	v_mov_b32_e32 v69, v1
	v_mov_b32_e32 v70, v1
	v_mov_b32_e32 v71, v1
	v_mov_b32_e32 v72, v1
	v_mov_b32_e32 v73, v1
	v_mov_b32_e32 v74, v1
	v_mov_b32_e32 v75, v1
	v_mov_b32_e32 v76, v1
	v_mov_b32_e32 v77, v1
	v_mov_b32_e32 v78, v1
	v_mov_b32_e32 v79, v1
	v_mov_b64_e32 v[48:49], v[64:65]
	v_mov_b64_e32 v[32:33], v[64:65]
	v_mov_b64_e32 v[16:17], v[64:65]
	v_mov_b32_e32 v197, v1
	s_or_b32 s21, s20, 31
	s_add_i32 s2, s3, 0xff
	s_addk_i32 s3, 0x100
	v_mov_b32_e32 v208, v14
	v_mov_b32_e32 v209, v14
	v_mov_b32_e32 v210, v14
	v_mov_b32_e32 v211, v14
	s_sub_i32 s34, 0xfe, s11
	v_sub_u32_e32 v205, v15, v198
	s_sub_i32 s22, 0x3fff, s10
	s_mov_b32 s23, 0
	s_mov_b64 s[36:37], 0
	v_mov_b32_e32 v222, 0
	v_mov_b64_e32 v[50:51], v[66:67]
	v_mov_b64_e32 v[52:53], v[68:69]
	v_mov_b64_e32 v[54:55], v[70:71]
	v_mov_b64_e32 v[56:57], v[72:73]
	v_mov_b64_e32 v[58:59], v[74:75]
	v_mov_b64_e32 v[60:61], v[76:77]
	v_mov_b64_e32 v[62:63], v[78:79]
	v_mov_b64_e32 v[34:35], v[66:67]
	v_mov_b64_e32 v[36:37], v[68:69]
	v_mov_b64_e32 v[38:39], v[70:71]
	v_mov_b64_e32 v[40:41], v[72:73]
	v_mov_b64_e32 v[42:43], v[74:75]
	v_mov_b64_e32 v[44:45], v[76:77]
	v_mov_b64_e32 v[46:47], v[78:79]
	v_mov_b64_e32 v[18:19], v[66:67]
	v_mov_b64_e32 v[20:21], v[68:69]
	v_mov_b64_e32 v[22:23], v[70:71]
	v_mov_b64_e32 v[24:25], v[72:73]
	v_mov_b64_e32 v[26:27], v[74:75]
	v_mov_b64_e32 v[28:29], v[76:77]
	v_mov_b64_e32 v[30:31], v[78:79]
	v_mov_b32_e32 v199, 0
	v_readlane_b32 s13, v255, 40
	s_andn2_b64 vcc, exec, s[40:41]
	s_cbranch_vccnz .Ld_fallback
	v_readfirstlane_b32 s100, v206
	v_readfirstlane_b32 s101, v207
	s_nop 1
	v_subrev_u32_e32 v243, s100, v206
	v_add_u32_e32 v244, v201, v194
	v_add_u32_e32 v245, 0xd800, v244
	v_add_u32_e32 v251, v203, v194
	v_add_u32_e32 v250, 0xd800, v251
	v_add_u32_e32 v248, 0xd800, v204
	v_add_u32_e32 v249, 0xd800, v200
	s_add_i32 s34, s34, -1
	s_waitcnt vmcnt(0)
	ds_write_b128 v204, v[224:227] offset:27648
	ds_write_b128 v200, v[228:231] offset:36864
	ds_write_b128 v200, v[232:235] offset:46080
	s_ashr_i32 s35, s34, 31
	s_lshl_b64 s[6:7], s[34:35], 17
	s_lshl_b64 s[10:11], s[34:35], 7
	s_add_u32 s10, s18, s10
	s_addc_u32 s11, s19, s11
	s_add_u32 s6, s6, s100
	s_addc_u32 s7, s7, s101
	global_load_dwordx4 v[148:151], v243, s[6:7]
	global_load_dwordx4 v[152:155], v0, s[10:11]
	global_load_dwordx4 v[156:159], v196, s[10:11]
	s_add_i32 s34, s34, -1
	s_mov_b32 s8, 0x42000000
	s_mov_b32 s9, 0x42040000
	s_sub_i32 s24, s22, s21
	s_ashr_i32 s24, s24, 6
	s_max_i32 s24, s24, 0
	s_waitcnt lgkmcnt(0)
	s_barrier
	s_cmp_lg_u32 s24, 0
	s_cbranch_scc1 .Ld_noqk0
	ds_read_b128 v[160:163], v244 offset:0
	ds_read_b128 v[164:167], v244 offset:32
	ds_read_b128 v[168:171], v244 offset:64
	ds_read_b128 v[172:175], v244 offset:96
	ds_read_b128 v[224:227], v244 offset:4608
	ds_read_b128 v[228:231], v244 offset:4640
	ds_read_b128 v[232:235], v244 offset:4672
	ds_read_b128 v[236:239], v244 offset:4704
	v_cvt_f32_i32_e32 v246, v205
	v_fma_f32 v242, -v14, v246, -v222
	v_mov_b32_e32 v80, v242
	v_add_f32_e32 v81, v14, v242
	v_fma_f32 v82, v14, s62, v242
	v_fma_f32 v83, v14, s63, v242
	v_fma_f32 v84, v14, s64, v242
	v_fma_f32 v85, v14, s65, v242
	v_fma_f32 v86, v14, s66, v242
	v_fma_f32 v87, v14, s67, v242
	v_fma_f32 v88, v14, s68, v242
	v_fma_f32 v89, v14, s69, v242
	v_fma_f32 v90, v14, s70, v242
	v_fma_f32 v91, v14, s71, v242
	v_fma_f32 v92, v14, s72, v242
	v_fma_f32 v93, v14, s73, v242
	v_fma_f32 v94, v14, s76, v242
	v_fma_f32 v95, v14, s77, v242
	v_fma_f32 v96, v14, s8, v242
	v_fma_f32 v97, v14, s9, v242
	v_fma_f32 v98, v14, s96, v242
	v_fma_f32 v99, v14, s97, v242
	v_fma_f32 v100, v14, s94, v242
	v_fma_f32 v101, v14, s95, v242
	v_fma_f32 v102, v14, s92, v242
	v_fma_f32 v103, v14, s93, v242
	v_fma_f32 v104, v14, s90, v242
	v_fma_f32 v105, v14, s91, v242
	v_fma_f32 v106, v14, s88, v242
	v_fma_f32 v107, v14, s89, v242
	v_fma_f32 v108, v14, s86, v242
	v_fma_f32 v109, v14, s87, v242
	v_fma_f32 v110, v14, s78, v242
	v_fma_f32 v111, v14, s79, v242
	s_waitcnt lgkmcnt(0)
	v_mfma_f32_32x32x16_bf16 v[80:95], v[160:163], v[2:5], v[80:95]
	v_mfma_f32_32x32x16_bf16 v[96:111], v[224:227], v[2:5], v[96:111]
	v_mfma_f32_32x32x16_bf16 v[80:95], v[164:167], v[6:9], v[80:95]
	v_mfma_f32_32x32x16_bf16 v[96:111], v[228:231], v[6:9], v[96:111]
	v_mfma_f32_32x32x16_bf16 v[80:95], v[168:171], v[10:13], v[80:95]
	v_mfma_f32_32x32x16_bf16 v[96:111], v[232:235], v[10:13], v[96:111]
	v_mfma_f32_32x32x16_bf16 v[80:95], v[172:175], v[144:147], v[80:95]
	v_mfma_f32_32x32x16_bf16 v[96:111], v[236:239], v[144:147], v[96:111]
; #define LAS __attribute__((address_space(3)))
; template <int DQK, int DV, int FLAGS, int qp, int kp, int vts, int op> ...
;     ...
;             if (FLAGS & AF_ALIBI) { const float ab = -slope2 * (float)nrel - ((FLAGS & AF_ROBUST) ? 0.f : m);
; #pragma unroll
;                 for (int r = 0; r < 16; ++r) { const float c = (float)(16 * (r >> 3) + (r & 7)); p0[r] = __builtin_fmaf(slope2, c, ab); p1[r] = __builtin_fmaf(slope2, c + 32.f, ab); }
;             } else if (FLAGS & AF_ROBUST) {
; #pragma unroll
;                 for (int r = 0; r < 16; ++r) { p0[r] = 0.f; p1[r] = 0.f; }
;             } else { p0 = negm; p1 = negm; }
;             __builtin_amdgcn_sched_barrier(0);
; #pragma unroll
;             for (int c = 0; c < ND0 / 2; ++c) {
;                 if (c + 1 < ND0 / 2) {
; #pragma unroll
;                     for (int i = 0; i < 2; ++i) { kf[(c + 1) & 1][2 * i] = *(const LAS bf16x8*)(kb + (2 * c + 2 + i) * 32); kf[(c + 1) & 1][2 * i + 1] = *(const LAS bf16x8*)(kb + 32 * KROW + (2 * c + 2 + i) * 32); }
;                 }
; #pragma unroll
;                 for (int i = 0; i < 2; ++i) {
;                     p0 = __builtin_amdgcn_mfma_f32_32x32x16_bf16(kf[c & 1][2 * i], qr[2 * c + i], p0, 0, 0, 0);
;                     p1 = __builtin_amdgcn_mfma_f32_32x32x16_bf16(kf[c & 1][2 * i + 1], qr[2 * c + i], p1, 0, 0, 0);
;                 }
;                 __builtin_amdgcn_sched_barrier(0);
;             }
;     ...
;             f32x2 rs2 = {0.f, 0.f};
; #pragma unroll
;             for (int r = 0; r < 16; ++r) { p0[r] = __builtin_amdgcn_exp2f(p0[r]); p1[r] = __builtin_amdgcn_exp2f(p1[r]); }
; #pragma unroll
;             for (int r = 0; r < 16; r += 2) { rs2 += (f32x2){p0[r], p0[r + 1]}; rs2 += (f32x2){p1[r], p1[r + 1]}; }
;             l += rs2.x + rs2.y;
;             bf16x8 pf[4];
;             pf[0] = pack_bf16x8(p0, 0); pf[1] = pack_bf16x8(p0, 8); pf[2] = pack_bf16x8(p1, 0); pf[3] = pack_bf16x8(p1, 8);
;             __builtin_amdgcn_sched_barrier(0);
; #pragma unroll
;             for (int d = 0; d < NDB; ++d) {
;                 if (d + 1 < NDB) {
; #pragma unroll
;                     for (int ks = 0; ks < 4; ++ks) vf[(d + 1) & 1][ks] = *(const LAS bf16x8*)(vb + (d + 1) * 32 * VROW + ks * 32);
;                 }
; #pragma unroll
;                 for (int ks = 0; ks < 4; ++ks) o[d] = __builtin_amdgcn_mfma_f32_32x32x16_bf16(vf[d & 1][ks], pf[ks], o[d], 0, 0, 0);
.Ld_noqk0:
.Ld_top0:
	s_cmp_le_i32 s23, s24
	s_cbranch_scc1 .Ld_gen0
	s_add_i32 s13, s23, 1
	s_cmp_ge_i32 s13, s3
	s_cbranch_scc1 .Ld_gen0
	ds_read_b128 v[224:227], v250 offset:41472
	ds_read_b128 v[228:231], v250 offset:41504
	ds_read_b128 v[232:235], v250 offset:41536
	ds_read_b128 v[236:239], v250 offset:41568
	v_mfma_f32_32x32x16_bf16 v[64:79], v[160:163], v[112:115], v[64:79]
	v_exp_f32_e32 v80, v80
	v_exp_f32_e32 v81, v81
	v_exp_f32_e32 v96, v96
	v_exp_f32_e32 v97, v97
	v_add_u32_e32 v246, 64, v205
	v_mfma_f32_32x32x16_bf16 v[64:79], v[164:167], v[116:119], v[64:79]
	v_add_f32_e32 v240, v80, v199
	v_exp_f32_e32 v82, v82
	v_exp_f32_e32 v83, v83
	v_add_f32_e32 v240, v96, v240
	v_cvt_f32_i32_e32 v246, v246
	v_mfma_f32_32x32x16_bf16 v[64:79], v[168:171], v[120:123], v[64:79]
	v_add_f32_e32 v241, v81, v97
	v_exp_f32_e32 v98, v98
	v_exp_f32_e32 v99, v99
	v_add_f32_e32 v240, v82, v240
	v_fma_f32 v242, -v14, v246, -v222
	v_mfma_f32_32x32x16_bf16 v[64:79], v[172:175], v[124:127], v[64:79]
	v_add_f32_e32 v241, v83, v241
	v_exp_f32_e32 v84, v84
	v_exp_f32_e32 v85, v85
	v_add_f32_e32 v240, v98, v240
	v_fma_f32 v128, v14, s8, v242
	ds_read_b128 v[160:163], v250 offset:46080
	ds_read_b128 v[164:167], v250 offset:46112
	ds_read_b128 v[168:171], v250 offset:46144
	ds_read_b128 v[172:175], v250 offset:46176
	s_waitcnt lgkmcnt(4)
	v_mfma_f32_32x32x16_bf16 v[48:63], v[224:227], v[112:115], v[48:63]
	v_add_f32_e32 v241, v99, v241
	v_exp_f32_e32 v100, v100
	v_exp_f32_e32 v101, v101
	v_add_f32_e32 v240, v84, v240
	v_fma_f32 v129, v14, s9, v242
	s_waitcnt vmcnt(0)
	ds_write_b128 v248, v[148:151] offset:0
	v_mfma_f32_32x32x16_bf16 v[48:63], v[228:231], v[116:119], v[48:63]
	v_add_f32_e32 v241, v85, v241
	v_exp_f32_e32 v86, v86
	v_exp_f32_e32 v87, v87
	v_add_f32_e32 v240, v100, v240
	v_fma_f32 v130, v14, s96, v242
	ds_write_b128 v249, v[152:155] offset:9216
	v_mfma_f32_32x32x16_bf16 v[48:63], v[232:235], v[120:123], v[48:63]
	v_add_f32_e32 v241, v101, v241
	v_exp_f32_e32 v102, v102
	v_exp_f32_e32 v103, v103
	v_add_f32_e32 v240, v86, v240
	v_fma_f32 v131, v14, s97, v242
	ds_write_b128 v249, v[156:159] offset:18432
	v_mfma_f32_32x32x16_bf16 v[48:63], v[236:239], v[124:127], v[48:63]
	v_add_f32_e32 v241, v87, v241
	v_exp_f32_e32 v88, v88
	v_exp_f32_e32 v89, v89
	v_add_f32_e32 v240, v102, v240
	v_fma_f32 v132, v14, s94, v242
	ds_read_b128 v[224:227], v250 offset:50688
	ds_read_b128 v[228:231], v250 offset:50720
	ds_read_b128 v[232:235], v250 offset:50752
	ds_read_b128 v[236:239], v250 offset:50784
	s_waitcnt lgkmcnt(4)
	v_mfma_f32_32x32x16_bf16 v[32:47], v[160:163], v[112:115], v[32:47]
	v_add_f32_e32 v241, v103, v241
	v_exp_f32_e32 v104, v104
	v_exp_f32_e32 v105, v105
	v_add_f32_e32 v240, v88, v240
	v_fma_f32 v133, v14, s95, v242
	v_mfma_f32_32x32x16_bf16 v[32:47], v[164:167], v[116:119], v[32:47]
	v_add_f32_e32 v241, v89, v241
	v_exp_f32_e32 v90, v90
	v_exp_f32_e32 v91, v91
	v_add_f32_e32 v240, v104, v240
	v_fma_f32 v134, v14, s92, v242
	s_ashr_i32 s35, s34, 31
	s_lshl_b64 s[6:7], s[34:35], 17
	s_lshl_b64 s[10:11], s[34:35], 7
	s_add_u32 s10, s18, s10
	s_addc_u32 s11, s19, s11
	s_add_u32 s6, s6, s100
	s_addc_u32 s7, s7, s101
	global_load_dwordx4 v[148:151], v243, s[6:7]
	v_mfma_f32_32x32x16_bf16 v[32:47], v[168:171], v[120:123], v[32:47]
	v_add_f32_e32 v241, v105, v241
	v_exp_f32_e32 v106, v106
	v_exp_f32_e32 v107, v107
	v_add_f32_e32 v240, v90, v240
	v_fma_f32 v135, v14, s93, v242
	global_load_dwordx4 v[152:155], v0, s[10:11]
	v_mfma_f32_32x32x16_bf16 v[32:47], v[172:175], v[124:127], v[32:47]
	v_add_f32_e32 v241, v91, v241
	v_exp_f32_e32 v92, v92
	v_exp_f32_e32 v93, v93
	v_add_f32_e32 v240, v106, v240
	v_fma_f32 v136, v14, s90, v242
	global_load_dwordx4 v[156:159], v196, s[10:11]
	s_add_i32 s34, s34, -1
	ds_read_b128 v[160:163], v244 offset:32256
	ds_read_b128 v[164:167], v244 offset:32288
	ds_read_b128 v[168:171], v244 offset:32320
	ds_read_b128 v[172:175], v244 offset:32352
	s_waitcnt lgkmcnt(4)
	v_mfma_f32_32x32x16_bf16 v[16:31], v[224:227], v[112:115], v[16:31]
	v_add_f32_e32 v241, v107, v241
	v_exp_f32_e32 v108, v108
	v_exp_f32_e32 v109, v109
	v_add_f32_e32 v240, v92, v240
	v_fma_f32 v137, v14, s91, v242
	v_mfma_f32_32x32x16_bf16 v[16:31], v[228:231], v[116:119], v[16:31]
	v_add_f32_e32 v241, v93, v241
	v_exp_f32_e32 v94, v94
	v_exp_f32_e32 v95, v95
	v_add_f32_e32 v240, v108, v240
	v_fma_f32 v138, v14, s88, v242
	v_mfma_f32_32x32x16_bf16 v[16:31], v[232:235], v[120:123], v[16:31]
	v_add_f32_e32 v241, v109, v241
	v_exp_f32_e32 v110, v110
	v_exp_f32_e32 v111, v111
	v_add_f32_e32 v240, v94, v240
	v_fma_f32 v139, v14, s89, v242
	v_mfma_f32_32x32x16_bf16 v[16:31], v[236:239], v[124:127], v[16:31]
	v_add_f32_e32 v241, v95, v241
	v_fma_f32 v140, v14, s86, v242
	v_fma_f32 v141, v14, s87, v242
	v_fma_f32 v142, v14, s78, v242
	v_fma_f32 v143, v14, s79, v242
	ds_read_b128 v[224:227], v244 offset:27648
	ds_read_b128 v[228:231], v244 offset:27680
	ds_read_b128 v[232:235], v244 offset:27712
	ds_read_b128 v[236:239], v244 offset:27744
	s_waitcnt lgkmcnt(4)
	v_mfma_f32_32x32x16_bf16 v[128:143], v[160:163], v[2:5], v[128:143]
	v_mov_b32_e32 v112, v242
	v_add_f32_e32 v113, v14, v242
	v_fma_f32 v114, v14, s62, v242
	v_fma_f32 v115, v14, s63, v242
	v_mfma_f32_32x32x16_bf16 v[128:143], v[164:167], v[6:9], v[128:143]
	v_fma_f32 v116, v14, s64, v242
	v_fma_f32 v117, v14, s65, v242
	v_fma_f32 v118, v14, s66, v242
	v_fma_f32 v119, v14, s67, v242
	v_mfma_f32_32x32x16_bf16 v[128:143], v[168:171], v[10:13], v[128:143]
	v_fma_f32 v120, v14, s68, v242
	v_fma_f32 v121, v14, s69, v242
	v_fma_f32 v122, v14, s70, v242
	v_fma_f32 v123, v14, s71, v242
	v_mfma_f32_32x32x16_bf16 v[128:143], v[172:175], v[144:147], v[128:143]
	v_fma_f32 v124, v14, s72, v242
	v_fma_f32 v125, v14, s73, v242
	v_fma_f32 v126, v14, s76, v242
	v_fma_f32 v127, v14, s77, v242
	ds_read_b128 v[160:163], v251 offset:9216
	ds_read_b128 v[164:167], v251 offset:9248
	ds_read_b128 v[168:171], v251 offset:9280
	ds_read_b128 v[172:175], v251 offset:9312
	s_waitcnt lgkmcnt(4)
	v_mfma_f32_32x32x16_bf16 v[112:127], v[224:227], v[2:5], v[112:127]
	s_nop 0
	v_add_f32_e32 v240, v110, v240
	v_add_f32_e32 v241, v111, v241
	v_cvt_pk_bf16_f32 v80, v80, v81
	v_cvt_pk_bf16_f32 v81, v82, v83
	v_cvt_pk_bf16_f32 v82, v84, v85
	v_mfma_f32_32x32x16_bf16 v[112:127], v[228:231], v[6:9], v[112:127]
	v_cvt_pk_bf16_f32 v83, v86, v87
	v_cvt_pk_bf16_f32 v84, v88, v89
	v_cvt_pk_bf16_f32 v85, v90, v91
	v_cvt_pk_bf16_f32 v86, v92, v93
	v_cvt_pk_bf16_f32 v87, v94, v95
	v_cvt_pk_bf16_f32 v88, v96, v97
	v_mfma_f32_32x32x16_bf16 v[112:127], v[232:235], v[10:13], v[112:127]
	v_cvt_pk_bf16_f32 v89, v98, v99
	v_cvt_pk_bf16_f32 v90, v100, v101
	v_cvt_pk_bf16_f32 v91, v102, v103
	v_cvt_pk_bf16_f32 v92, v104, v105
	v_cvt_pk_bf16_f32 v93, v106, v107
	v_cvt_pk_bf16_f32 v94, v108, v109
	v_mfma_f32_32x32x16_bf16 v[112:127], v[236:239], v[144:147], v[112:127]
	v_cvt_pk_bf16_f32 v95, v110, v111
	v_add_f32_e32 v199, v240, v241
	s_branch .Ld_tail0
; #define LAS __attribute__((address_space(3)))
; template <int DQK, int DV, int FLAGS, int qp, int kp, int vts, int op> ...
;     ...
;             for (int d = 0; d < NDB; ++d) {
;                 if (d + 1 < NDB) {
; #pragma unroll
;                     for (int ks = 0; ks < 4; ++ks) vf[(d + 1) & 1][ks] = *(const LAS bf16x8*)(vb + (d + 1) * 32 * VROW + ks * 32);
;                 }
; #pragma unroll
;                 for (int ks = 0; ks < 4; ++ks) o[d] = __builtin_amdgcn_mfma_f32_32x32x16_bf16(vf[d & 1][ks], pf[ks], o[d], 0, 0, 0);
;                 __builtin_amdgcn_sched_barrier(0);
;             }
.Ld_gen0:
	s_add_i32 s12, s23, 2
	s_cmp_ge_i32 s12, s3
	s_cbranch_scc1 .Ld_nols_q0
	s_and_b32 s13, s12, 3
	s_mulk_i32 s13, 0x6c00
	s_waitcnt vmcnt(0)
	v_add_u32_e32 v246, s13, v204
	ds_write_b128 v246, v[148:151]
	v_add_u32_e32 v246, s13, v200
	ds_write_b128 v246, v[152:155] offset:9216
	ds_write_b128 v246, v[156:159] offset:18432
	s_add_i32 s12, s23, 3
	s_cmp_ge_i32 s12, s3
	s_cbranch_scc1 .Ld_nols_q0
	s_ashr_i32 s35, s34, 31
	s_lshl_b64 s[6:7], s[34:35], 17
	s_lshl_b64 s[10:11], s[34:35], 7
	s_add_u32 s10, s18, s10
	s_addc_u32 s11, s19, s11
	s_add_u32 s6, s6, s100
	s_addc_u32 s7, s7, s101
	global_load_dwordx4 v[148:151], v243, s[6:7]
	global_load_dwordx4 v[152:155], v0, s[10:11]
	global_load_dwordx4 v[156:159], v196, s[10:11]
	s_add_i32 s34, s34, -1
.Ld_nols_q0:
	s_cmp_le_i32 s23, s24
	s_cbranch_scc1 .Ld_nopv_q0
	s_waitcnt lgkmcnt(0)
	s_add_i32 s12, s23, -1
	s_and_b32 s12, s12, 3
	s_mulk_i32 s12, 0x6c00
	v_add3_u32 v246, s12, v203, v194
	ds_read_b128 v[224:227], v246 offset:13824
	ds_read_b128 v[228:231], v246 offset:13856
	ds_read_b128 v[232:235], v246 offset:13888
	ds_read_b128 v[236:239], v246 offset:13920
	v_mfma_f32_32x32x16_bf16 v[64:79], v[160:163], v[112:115], v[64:79]
	v_mfma_f32_32x32x16_bf16 v[64:79], v[164:167], v[116:119], v[64:79]
	v_mfma_f32_32x32x16_bf16 v[64:79], v[168:171], v[120:123], v[64:79]
	v_mfma_f32_32x32x16_bf16 v[64:79], v[172:175], v[124:127], v[64:79]
	ds_read_b128 v[160:163], v246 offset:18432
	ds_read_b128 v[164:167], v246 offset:18464
	ds_read_b128 v[168:171], v246 offset:18496
	ds_read_b128 v[172:175], v246 offset:18528
	s_waitcnt lgkmcnt(4)
	v_mfma_f32_32x32x16_bf16 v[48:63], v[224:227], v[112:115], v[48:63]
	v_mfma_f32_32x32x16_bf16 v[48:63], v[228:231], v[116:119], v[48:63]
	v_mfma_f32_32x32x16_bf16 v[48:63], v[232:235], v[120:123], v[48:63]
	v_mfma_f32_32x32x16_bf16 v[48:63], v[236:239], v[124:127], v[48:63]
	ds_read_b128 v[224:227], v246 offset:23040
	ds_read_b128 v[228:231], v246 offset:23072
	ds_read_b128 v[232:235], v246 offset:23104
	ds_read_b128 v[236:239], v246 offset:23136
	s_waitcnt lgkmcnt(4)
	v_mfma_f32_32x32x16_bf16 v[32:47], v[160:163], v[112:115], v[32:47]
	v_mfma_f32_32x32x16_bf16 v[32:47], v[164:167], v[116:119], v[32:47]
	v_mfma_f32_32x32x16_bf16 v[32:47], v[168:171], v[120:123], v[32:47]
	v_mfma_f32_32x32x16_bf16 v[32:47], v[172:175], v[124:127], v[32:47]
	s_waitcnt lgkmcnt(0)
	v_mfma_f32_32x32x16_bf16 v[16:31], v[224:227], v[112:115], v[16:31]
	v_mfma_f32_32x32x16_bf16 v[16:31], v[228:231], v[116:119], v[16:31]
	v_mfma_f32_32x32x16_bf16 v[16:31], v[232:235], v[120:123], v[16:31]
	v_mfma_f32_32x32x16_bf16 v[16:31], v[236:239], v[124:127], v[16:31]

; #define LAS __attribute__((address_space(3)))
; template <int DQK, int DV, int FLAGS, int qp, int kp, int vts, int op> ...
;     ...
;             if (FLAGS & AF_ALIBI) { const float ab = -slope2 * (float)nrel - ((FLAGS & AF_ROBUST) ? 0.f : m);
; #pragma unroll
;                 for (int r = 0; r < 16; ++r) { const float c = (float)(16 * (r >> 3) + (r & 7)); p0[r] = __builtin_fmaf(slope2, c, ab); p1[r] = __builtin_fmaf(slope2, c + 32.f, ab); }
;             } else if (FLAGS & AF_ROBUST) {
; #pragma unroll
;                 for (int r = 0; r < 16; ++r) { p0[r] = 0.f; p1[r] = 0.f; }
;             } else { p0 = negm; p1 = negm; }
;             __builtin_amdgcn_sched_barrier(0);
; #pragma unroll
;             for (int c = 0; c < ND0 / 2; ++c) {
;                 if (c + 1 < ND0 / 2) {
; #pragma unroll
;                     for (int i = 0; i < 2; ++i) { kf[(c + 1) & 1][2 * i] = *(const LAS bf16x8*)(kb + (2 * c + 2 + i) * 32); kf[(c + 1) & 1][2 * i + 1] = *(const LAS bf16x8*)(kb + 32 * KROW + (2 * c + 2 + i) * 32); }
;                 }
; #pragma unroll
;                 for (int i = 0; i < 2; ++i) {
;                     p0 = __builtin_amdgcn_mfma_f32_32x32x16_bf16(kf[c & 1][2 * i], qr[2 * c + i], p0, 0, 0, 0);
;                     p1 = __builtin_amdgcn_mfma_f32_32x32x16_bf16(kf[c & 1][2 * i + 1], qr[2 * c + i], p1, 0, 0, 0);
;                 }
;                 __builtin_amdgcn_sched_barrier(0);
;             }
;     ...
;             f32x2 rs2 = {0.f, 0.f};
; #pragma unroll
;             for (int r = 0; r < 16; ++r) { p0[r] = __builtin_amdgcn_exp2f(p0[r]); p1[r] = __builtin_amdgcn_exp2f(p1[r]); }
; #pragma unroll
;             for (int r = 0; r < 16; r += 2) { rs2 += (f32x2){p0[r], p0[r + 1]}; rs2 += (f32x2){p1[r], p1[r + 1]}; }
;             l += rs2.x + rs2.y;
;             bf16x8 pf[4];
;             pf[0] = pack_bf16x8(p0, 0); pf[1] = pack_bf16x8(p0, 8); pf[2] = pack_bf16x8(p1, 0); pf[3] = pack_bf16x8(p1, 8);
.Ld_notfirst_q0:
	v_exp_f32_e32 v80, v80
	v_exp_f32_e32 v81, v81
	v_exp_f32_e32 v96, v96
	v_exp_f32_e32 v97, v97
	v_add_f32_e32 v240, v80, v199
	v_exp_f32_e32 v82, v82
	v_exp_f32_e32 v83, v83
	v_add_f32_e32 v240, v96, v240
	v_add_f32_e32 v241, v81, v97
	v_exp_f32_e32 v98, v98
	v_exp_f32_e32 v99, v99
	v_add_f32_e32 v240, v82, v240
	v_add_f32_e32 v241, v83, v241
	v_exp_f32_e32 v84, v84
	v_exp_f32_e32 v85, v85
	v_add_f32_e32 v240, v98, v240
	v_add_f32_e32 v241, v99, v241
	v_exp_f32_e32 v100, v100
	v_exp_f32_e32 v101, v101
	v_add_f32_e32 v240, v84, v240
	v_add_f32_e32 v241, v85, v241
	v_exp_f32_e32 v86, v86
	v_exp_f32_e32 v87, v87
	v_add_f32_e32 v240, v100, v240
	v_add_f32_e32 v241, v101, v241
	v_exp_f32_e32 v102, v102
	v_exp_f32_e32 v103, v103
	v_add_f32_e32 v240, v86, v240
	v_add_f32_e32 v241, v87, v241
	v_exp_f32_e32 v88, v88
	v_exp_f32_e32 v89, v89
	v_add_f32_e32 v240, v102, v240
	v_add_f32_e32 v241, v103, v241
	v_exp_f32_e32 v104, v104
	v_exp_f32_e32 v105, v105
	v_add_f32_e32 v240, v88, v240
	v_add_f32_e32 v241, v89, v241
	v_exp_f32_e32 v90, v90
	v_exp_f32_e32 v91, v91
	v_add_f32_e32 v240, v104, v240
	v_add_f32_e32 v241, v105, v241
	v_exp_f32_e32 v106, v106
	v_exp_f32_e32 v107, v107
	v_add_f32_e32 v240, v90, v240
	v_add_f32_e32 v241, v91, v241
	v_exp_f32_e32 v92, v92
	v_exp_f32_e32 v93, v93
	v_add_f32_e32 v240, v106, v240
	v_add_f32_e32 v241, v107, v241
	v_exp_f32_e32 v108, v108
	v_exp_f32_e32 v109, v109
	v_add_f32_e32 v240, v92, v240
	v_add_f32_e32 v241, v93, v241
	v_exp_f32_e32 v94, v94
	v_exp_f32_e32 v95, v95
	v_add_f32_e32 v240, v108, v240
	v_add_f32_e32 v241, v109, v241
	v_exp_f32_e32 v110, v110
	v_exp_f32_e32 v111, v111
	v_add_f32_e32 v240, v94, v240
	v_add_f32_e32 v241, v95, v241
	s_nop 0
	v_add_f32_e32 v240, v110, v240
	v_add_f32_e32 v241, v111, v241
	v_cvt_pk_bf16_f32 v80, v80, v81
	v_cvt_pk_bf16_f32 v81, v82, v83
	v_cvt_pk_bf16_f32 v82, v84, v85
	v_cvt_pk_bf16_f32 v83, v86, v87
	v_cvt_pk_bf16_f32 v84, v88, v89
	v_cvt_pk_bf16_f32 v85, v90, v91
	v_cvt_pk_bf16_f32 v86, v92, v93
	v_cvt_pk_bf16_f32 v87, v94, v95
	v_cvt_pk_bf16_f32 v88, v96, v97
	v_cvt_pk_bf16_f32 v89, v98, v99
	v_cvt_pk_bf16_f32 v90, v100, v101
	v_cvt_pk_bf16_f32 v91, v102, v103
	v_cvt_pk_bf16_f32 v92, v104, v105
	v_cvt_pk_bf16_f32 v93, v106, v107
	v_cvt_pk_bf16_f32 v94, v108, v109
	v_cvt_pk_bf16_f32 v95, v110, v111
	v_add_f32_e32 v199, v240, v241
.Ld_nosm_q0:
	s_add_i32 s13, s23, 1
	s_cmp_ge_i32 s13, s3
	s_cbranch_scc1 .Ld_noqk_q0
	s_cmp_lt_i32 s13, s24
	s_cbranch_scc1 .Ld_noqk_q0
	s_add_i32 s12, s23, 1
	s_and_b32 s12, s12, 3
	s_mulk_i32 s12, 0x6c00
	v_add3_u32 v247, s12, v201, v194
	ds_read_b128 v[160:163], v247 offset:0
	ds_read_b128 v[164:167], v247 offset:32
	ds_read_b128 v[168:171], v247 offset:64
	ds_read_b128 v[172:175], v247 offset:96
	ds_read_b128 v[224:227], v247 offset:4608
	ds_read_b128 v[228:231], v247 offset:4640
	ds_read_b128 v[232:235], v247 offset:4672
	ds_read_b128 v[236:239], v247 offset:4704
	v_add_u32_e32 v246, 64, v205
	v_cvt_f32_i32_e32 v246, v246
	v_fma_f32 v242, -v14, v246, -v222
	v_mov_b32_e32 v112, v242
	v_add_f32_e32 v113, v14, v242
	v_fma_f32 v114, v14, s62, v242
	v_fma_f32 v115, v14, s63, v242
	v_fma_f32 v116, v14, s64, v242
	v_fma_f32 v117, v14, s65, v242
	v_fma_f32 v118, v14, s66, v242
	v_fma_f32 v119, v14, s67, v242
	v_fma_f32 v120, v14, s68, v242
	v_fma_f32 v121, v14, s69, v242
	v_fma_f32 v122, v14, s70, v242
	v_fma_f32 v123, v14, s71, v242
	v_fma_f32 v124, v14, s72, v242
	v_fma_f32 v125, v14, s73, v242
	v_fma_f32 v126, v14, s76, v242
	v_fma_f32 v127, v14, s77, v242
	v_fma_f32 v128, v14, s8, v242
	v_fma_f32 v129, v14, s9, v242
	v_fma_f32 v130, v14, s96, v242
	v_fma_f32 v131, v14, s97, v242
	v_fma_f32 v132, v14, s94, v242
	v_fma_f32 v133, v14, s95, v242
	v_fma_f32 v134, v14, s92, v242
	v_fma_f32 v135, v14, s93, v242
	v_fma_f32 v136, v14, s90, v242
	v_fma_f32 v137, v14, s91, v242
	v_fma_f32 v138, v14, s88, v242
	v_fma_f32 v139, v14, s89, v242
	v_fma_f32 v140, v14, s86, v242
	v_fma_f32 v141, v14, s87, v242
	v_fma_f32 v142, v14, s78, v242
	v_fma_f32 v143, v14, s79, v242
	s_waitcnt lgkmcnt(0)
	v_mfma_f32_32x32x16_bf16 v[112:127], v[160:163], v[2:5], v[112:127]
	v_mfma_f32_32x32x16_bf16 v[128:143], v[224:227], v[2:5], v[128:143]
	v_mfma_f32_32x32x16_bf16 v[112:127], v[164:167], v[6:9], v[112:127]
	v_mfma_f32_32x32x16_bf16 v[128:143], v[228:231], v[6:9], v[128:143]
	v_mfma_f32_32x32x16_bf16 v[112:127], v[168:171], v[10:13], v[112:127]
	v_mfma_f32_32x32x16_bf16 v[128:143], v[232:235], v[10:13], v[128:143]
	v_mfma_f32_32x32x16_bf16 v[112:127], v[172:175], v[144:147], v[112:127]
	v_mfma_f32_32x32x16_bf16 v[128:143], v[236:239], v[144:147], v[128:143]
.Ld_noqk_q0:
	s_cmp_lt_i32 s23, s24
	s_cbranch_scc1 .Ld_nopre_q0
	s_and_b32 s12, s23, 3
	s_mulk_i32 s12, 0x6c00
	v_add3_u32 v246, s12, v203, v194
	ds_read_b128 v[160:163], v246 offset:9216
	ds_read_b128 v[164:167], v246 offset:9248
	ds_read_b128 v[168:171], v246 offset:9280
	ds_read_b128 v[172:175], v246 offset:9312

; #define LAS __attribute__((address_space(3)))
; template <int DQK, int DV, int FLAGS, int qp, int kp, int vts, int op> ...
;     ...
;             if (FLAGS & AF_ALIBI) { const float ab = -slope2 * (float)nrel - ((FLAGS & AF_ROBUST) ? 0.f : m);
; #pragma unroll
;                 for (int r = 0; r < 16; ++r) { const float c = (float)(16 * (r >> 3) + (r & 7)); p0[r] = __builtin_fmaf(slope2, c, ab); p1[r] = __builtin_fmaf(slope2, c + 32.f, ab); }
;             } else if (FLAGS & AF_ROBUST) {
; #pragma unroll
;                 for (int r = 0; r < 16; ++r) { p0[r] = 0.f; p1[r] = 0.f; }
;             } else { p0 = negm; p1 = negm; }
;             __builtin_amdgcn_sched_barrier(0);
; #pragma unroll
;             for (int c = 0; c < ND0 / 2; ++c) {
;                 if (c + 1 < ND0 / 2) {
; #pragma unroll
;                     for (int i = 0; i < 2; ++i) { kf[(c + 1) & 1][2 * i] = *(const LAS bf16x8*)(kb + (2 * c + 2 + i) * 32); kf[(c + 1) & 1][2 * i + 1] = *(const LAS bf16x8*)(kb + 32 * KROW + (2 * c + 2 + i) * 32); }
;                 }
; #pragma unroll
;                 for (int i = 0; i < 2; ++i) {
;                     p0 = __builtin_amdgcn_mfma_f32_32x32x16_bf16(kf[c & 1][2 * i], qr[2 * c + i], p0, 0, 0, 0);
;                     p1 = __builtin_amdgcn_mfma_f32_32x32x16_bf16(kf[c & 1][2 * i + 1], qr[2 * c + i], p1, 0, 0, 0);
;                 }
;                 __builtin_amdgcn_sched_barrier(0);
;             }
;             if (more) ATT_GLOAD((FLAGS & AF_REV) ? t - 1 : t + 1);
;     ...
;             f32x2 rs2 = {0.f, 0.f};
; #pragma unroll
;             for (int r = 0; r < 16; ++r) { p0[r] = __builtin_amdgcn_exp2f(p0[r]); p1[r] = __builtin_amdgcn_exp2f(p1[r]); }
; #pragma unroll
;             for (int r = 0; r < 16; r += 2) { rs2 += (f32x2){p0[r], p0[r + 1]}; rs2 += (f32x2){p1[r], p1[r + 1]}; }
;             l += rs2.x + rs2.y;
;             bf16x8 pf[4];
;             pf[0] = pack_bf16x8(p0, 0); pf[1] = pack_bf16x8(p0, 8); pf[2] = pack_bf16x8(p1, 0); pf[3] = pack_bf16x8(p1, 8);
;             __builtin_amdgcn_sched_barrier(0);
; #pragma unroll
;             for (int d = 0; d < NDB; ++d) {
;                 if (d + 1 < NDB) {
; #pragma unroll
;                     for (int ks = 0; ks < 4; ++ks) vf[(d + 1) & 1][ks] = *(const LAS bf16x8*)(vb + (d + 1) * 32 * VROW + ks * 32);
;                 }
; #pragma unroll
.Ld_top1:
	s_cmp_le_i32 s23, s24
	s_cbranch_scc1 .Ld_gen1
	s_add_i32 s13, s23, 1
	s_cmp_ge_i32 s13, s3
	s_cbranch_scc1 .Ld_gen1
	ds_read_b128 v[224:227], v251 offset:13824
	ds_read_b128 v[228:231], v251 offset:13856
	ds_read_b128 v[232:235], v251 offset:13888
	ds_read_b128 v[236:239], v251 offset:13920
	v_mfma_f32_32x32x16_bf16 v[64:79], v[160:163], v[80:83], v[64:79]
	v_exp_f32_e32 v112, v112
	v_exp_f32_e32 v113, v113
	v_exp_f32_e32 v128, v128
	v_exp_f32_e32 v129, v129
	v_add_u32_e32 v246, 64, v205
	v_mfma_f32_32x32x16_bf16 v[64:79], v[164:167], v[84:87], v[64:79]
	v_add_f32_e32 v240, v112, v199
	v_exp_f32_e32 v114, v114
	v_exp_f32_e32 v115, v115
	v_add_f32_e32 v240, v128, v240
	v_cvt_f32_i32_e32 v246, v246
	v_mfma_f32_32x32x16_bf16 v[64:79], v[168:171], v[88:91], v[64:79]
	v_add_f32_e32 v241, v113, v129
	v_exp_f32_e32 v130, v130
	v_exp_f32_e32 v131, v131
	v_add_f32_e32 v240, v114, v240
	v_fma_f32 v242, -v14, v246, -v222
	v_mfma_f32_32x32x16_bf16 v[64:79], v[172:175], v[92:95], v[64:79]
	v_add_f32_e32 v241, v115, v241
	v_exp_f32_e32 v116, v116
	v_exp_f32_e32 v117, v117
	v_add_f32_e32 v240, v130, v240
	v_fma_f32 v96, v14, s8, v242
	ds_read_b128 v[160:163], v251 offset:18432
	ds_read_b128 v[164:167], v251 offset:18464
	ds_read_b128 v[168:171], v251 offset:18496
	ds_read_b128 v[172:175], v251 offset:18528
	s_waitcnt lgkmcnt(4)
	v_mfma_f32_32x32x16_bf16 v[48:63], v[224:227], v[80:83], v[48:63]
	v_add_f32_e32 v241, v131, v241
	v_exp_f32_e32 v132, v132
	v_exp_f32_e32 v133, v133
	v_add_f32_e32 v240, v116, v240
	v_fma_f32 v97, v14, s9, v242
	s_waitcnt vmcnt(0)
	ds_write_b128 v248, v[148:151] offset:27648
	v_mfma_f32_32x32x16_bf16 v[48:63], v[228:231], v[84:87], v[48:63]
	v_add_f32_e32 v241, v117, v241
	v_exp_f32_e32 v118, v118
	v_exp_f32_e32 v119, v119
	v_add_f32_e32 v240, v132, v240
	v_fma_f32 v98, v14, s96, v242
	ds_write_b128 v249, v[152:155] offset:36864
	v_mfma_f32_32x32x16_bf16 v[48:63], v[232:235], v[88:91], v[48:63]
	v_add_f32_e32 v241, v133, v241
	v_exp_f32_e32 v134, v134
	v_exp_f32_e32 v135, v135
	v_add_f32_e32 v240, v118, v240
	v_fma_f32 v99, v14, s97, v242
	ds_write_b128 v249, v[156:159] offset:46080
	v_mfma_f32_32x32x16_bf16 v[48:63], v[236:239], v[92:95], v[48:63]
	v_add_f32_e32 v241, v119, v241
	v_exp_f32_e32 v120, v120
	v_exp_f32_e32 v121, v121
	v_add_f32_e32 v240, v134, v240
	v_fma_f32 v100, v14, s94, v242
	ds_read_b128 v[224:227], v251 offset:23040
	ds_read_b128 v[228:231], v251 offset:23072
	ds_read_b128 v[232:235], v251 offset:23104
	ds_read_b128 v[236:239], v251 offset:23136
	s_waitcnt lgkmcnt(4)
	v_mfma_f32_32x32x16_bf16 v[32:47], v[160:163], v[80:83], v[32:47]
	v_add_f32_e32 v241, v135, v241
	v_exp_f32_e32 v136, v136
	v_exp_f32_e32 v137, v137
	v_add_f32_e32 v240, v120, v240
	v_fma_f32 v101, v14, s95, v242
	v_mfma_f32_32x32x16_bf16 v[32:47], v[164:167], v[84:87], v[32:47]
	v_add_f32_e32 v241, v121, v241
	v_exp_f32_e32 v122, v122
	v_exp_f32_e32 v123, v123
	v_add_f32_e32 v240, v136, v240
	v_fma_f32 v102, v14, s92, v242
	s_ashr_i32 s35, s34, 31
	s_lshl_b64 s[6:7], s[34:35], 17
	s_lshl_b64 s[10:11], s[34:35], 7
	s_add_u32 s10, s18, s10
	s_addc_u32 s11, s19, s11
	s_add_u32 s6, s6, s100
	s_addc_u32 s7, s7, s101
	global_load_dwordx4 v[148:151], v243, s[6:7]
	v_mfma_f32_32x32x16_bf16 v[32:47], v[168:171], v[88:91], v[32:47]
	v_add_f32_e32 v241, v137, v241
	v_exp_f32_e32 v138, v138
	v_exp_f32_e32 v139, v139
	v_add_f32_e32 v240, v122, v240
	v_fma_f32 v103, v14, s93, v242
	global_load_dwordx4 v[152:155], v0, s[10:11]
	v_mfma_f32_32x32x16_bf16 v[32:47], v[172:175], v[92:95], v[32:47]
	v_add_f32_e32 v241, v123, v241
	v_exp_f32_e32 v124, v124
	v_exp_f32_e32 v125, v125
	v_add_f32_e32 v240, v138, v240
	v_fma_f32 v104, v14, s90, v242
	global_load_dwordx4 v[156:159], v196, s[10:11]
	s_add_i32 s34, s34, -1
	ds_read_b128 v[160:163], v245 offset:4608
	ds_read_b128 v[164:167], v245 offset:4640
	ds_read_b128 v[168:171], v245 offset:4672
	ds_read_b128 v[172:175], v245 offset:4704
	s_waitcnt lgkmcnt(4)
	v_mfma_f32_32x32x16_bf16 v[16:31], v[224:227], v[80:83], v[16:31]
	v_add_f32_e32 v241, v139, v241
	v_exp_f32_e32 v140, v140
	v_exp_f32_e32 v141, v141
	v_add_f32_e32 v240, v124, v240
	v_fma_f32 v105, v14, s91, v242
	v_mfma_f32_32x32x16_bf16 v[16:31], v[228:231], v[84:87], v[16:31]
	v_add_f32_e32 v241, v125, v241
	v_exp_f32_e32 v126, v126
	v_exp_f32_e32 v127, v127
	v_add_f32_e32 v240, v140, v240
	v_fma_f32 v106, v14, s88, v242
	v_mfma_f32_32x32x16_bf16 v[16:31], v[232:235], v[88:91], v[16:31]
	v_add_f32_e32 v241, v141, v241
	v_exp_f32_e32 v142, v142
	v_exp_f32_e32 v143, v143
	v_add_f32_e32 v240, v126, v240
	v_fma_f32 v107, v14, s89, v242
	v_mfma_f32_32x32x16_bf16 v[16:31], v[236:239], v[92:95], v[16:31]
	v_add_f32_e32 v241, v127, v241
	v_fma_f32 v108, v14, s86, v242
	v_fma_f32 v109, v14, s87, v242
	v_fma_f32 v110, v14, s78, v242
	v_fma_f32 v111, v14, s79, v242
	ds_read_b128 v[224:227], v245 offset:0
	ds_read_b128 v[228:231], v245 offset:32
	ds_read_b128 v[232:235], v245 offset:64
	ds_read_b128 v[236:239], v245 offset:96
	s_waitcnt lgkmcnt(4)
	v_mfma_f32_32x32x16_bf16 v[96:111], v[160:163], v[2:5], v[96:111]
	v_mov_b32_e32 v80, v242
	v_add_f32_e32 v81, v14, v242
	v_fma_f32 v82, v14, s62, v242
	v_fma_f32 v83, v14, s63, v242
	v_mfma_f32_32x32x16_bf16 v[96:111], v[164:167], v[6:9], v[96:111]
	v_fma_f32 v84, v14, s64, v242
	v_fma_f32 v85, v14, s65, v242
	v_fma_f32 v86, v14, s66, v242
	v_fma_f32 v87, v14, s67, v242
	v_mfma_f32_32x32x16_bf16 v[96:111], v[168:171], v[10:13], v[96:111]
	v_fma_f32 v88, v14, s68, v242
	v_fma_f32 v89, v14, s69, v242
	v_fma_f32 v90, v14, s70, v242
	v_fma_f32 v91, v14, s71, v242
	v_mfma_f32_32x32x16_bf16 v[96:111], v[172:175], v[144:147], v[96:111]
	v_fma_f32 v92, v14, s72, v242
	v_fma_f32 v93, v14, s73, v242
	v_fma_f32 v94, v14, s76, v242
	v_fma_f32 v95, v14, s77, v242
	ds_read_b128 v[160:163], v251 offset:36864
	ds_read_b128 v[164:167], v251 offset:36896
	ds_read_b128 v[168:171], v251 offset:36928
	ds_read_b128 v[172:175], v251 offset:36960
	s_waitcnt lgkmcnt(4)
	v_mfma_f32_32x32x16_bf16 v[80:95], v[224:227], v[2:5], v[80:95]
	s_nop 0
	v_add_f32_e32 v240, v142, v240
	v_add_f32_e32 v241, v143, v241
	v_cvt_pk_bf16_f32 v112, v112, v113
	v_cvt_pk_bf16_f32 v113, v114, v115
	v_cvt_pk_bf16_f32 v114, v116, v117
	v_mfma_f32_32x32x16_bf16 v[80:95], v[228:231], v[6:9], v[80:95]
	v_cvt_pk_bf16_f32 v115, v118, v119
	v_cvt_pk_bf16_f32 v116, v120, v121
	v_cvt_pk_bf16_f32 v117, v122, v123
	v_cvt_pk_bf16_f32 v118, v124, v125
	v_cvt_pk_bf16_f32 v119, v126, v127
	v_cvt_pk_bf16_f32 v120, v128, v129
	v_mfma_f32_32x32x16_bf16 v[80:95], v[232:235], v[10:13], v[80:95]
	v_cvt_pk_bf16_f32 v121, v130, v131
	v_cvt_pk_bf16_f32 v122, v132, v133
	v_cvt_pk_bf16_f32 v123, v134, v135
	v_cvt_pk_bf16_f32 v124, v136, v137
	v_cvt_pk_bf16_f32 v125, v138, v139
	v_cvt_pk_bf16_f32 v126, v140, v141
	v_mfma_f32_32x32x16_bf16 v[80:95], v[236:239], v[144:147], v[80:95]
	v_cvt_pk_bf16_f32 v127, v142, v143
	v_add_f32_e32 v199, v240, v241
	s_branch .Ld_tail1

; #define LAS __attribute__((address_space(3)))
; template <int DQK, int DV, int FLAGS, int qp, int kp, int vts, int op> ...
;     ...
; #pragma unroll
;             for (int d = 0; d < NDB; ++d) {
;                 if (d + 1 < NDB) {
; #pragma unroll
;                     for (int ks = 0; ks < 4; ++ks) vf[(d + 1) & 1][ks] = *(const LAS bf16x8*)(vb + (d + 1) * 32 * VROW + ks * 32);
;                 }
; #pragma unroll
;                 for (int ks = 0; ks < 4; ++ks) o[d] = __builtin_amdgcn_mfma_f32_32x32x16_bf16(vf[d & 1][ks], pf[ks], o[d], 0, 0, 0);
;                 __builtin_amdgcn_sched_barrier(0);
;             }
.Ld_nols_q1:
	s_cmp_le_i32 s23, s24
	s_cbranch_scc1 .Ld_nopv_q1
	s_waitcnt lgkmcnt(0)
	s_add_i32 s12, s23, -1
	s_and_b32 s12, s12, 3
	s_mulk_i32 s12, 0x6c00
	v_add3_u32 v246, s12, v203, v194
	ds_read_b128 v[224:227], v246 offset:13824
	ds_read_b128 v[228:231], v246 offset:13856
	ds_read_b128 v[232:235], v246 offset:13888
	ds_read_b128 v[236:239], v246 offset:13920
	v_mfma_f32_32x32x16_bf16 v[64:79], v[160:163], v[80:83], v[64:79]
	v_mfma_f32_32x32x16_bf16 v[64:79], v[164:167], v[84:87], v[64:79]
	v_mfma_f32_32x32x16_bf16 v[64:79], v[168:171], v[88:91], v[64:79]
	v_mfma_f32_32x32x16_bf16 v[64:79], v[172:175], v[92:95], v[64:79]
	ds_read_b128 v[160:163], v246 offset:18432
	ds_read_b128 v[164:167], v246 offset:18464
	ds_read_b128 v[168:171], v246 offset:18496
	ds_read_b128 v[172:175], v246 offset:18528
	s_waitcnt lgkmcnt(4)
	v_mfma_f32_32x32x16_bf16 v[48:63], v[224:227], v[80:83], v[48:63]
	v_mfma_f32_32x32x16_bf16 v[48:63], v[228:231], v[84:87], v[48:63]
	v_mfma_f32_32x32x16_bf16 v[48:63], v[232:235], v[88:91], v[48:63]
	v_mfma_f32_32x32x16_bf16 v[48:63], v[236:239], v[92:95], v[48:63]
	ds_read_b128 v[224:227], v246 offset:23040
	ds_read_b128 v[228:231], v246 offset:23072
	ds_read_b128 v[232:235], v246 offset:23104
	ds_read_b128 v[236:239], v246 offset:23136
	s_waitcnt lgkmcnt(4)
	v_mfma_f32_32x32x16_bf16 v[32:47], v[160:163], v[80:83], v[32:47]
	v_mfma_f32_32x32x16_bf16 v[32:47], v[164:167], v[84:87], v[32:47]
	v_mfma_f32_32x32x16_bf16 v[32:47], v[168:171], v[88:91], v[32:47]
	v_mfma_f32_32x32x16_bf16 v[32:47], v[172:175], v[92:95], v[32:47]
	s_waitcnt lgkmcnt(0)
	v_mfma_f32_32x32x16_bf16 v[16:31], v[224:227], v[80:83], v[16:31]
	v_mfma_f32_32x32x16_bf16 v[16:31], v[228:231], v[84:87], v[16:31]
	v_mfma_f32_32x32x16_bf16 v[16:31], v[232:235], v[88:91], v[16:31]
	v_mfma_f32_32x32x16_bf16 v[16:31], v[236:239], v[92:95], v[16:31]

; #define LAS __attribute__((address_space(3)))
; template <int DQK, int DV, int FLAGS, int qp, int kp, int vts, int op> ...
;     ...
;             if (FLAGS & AF_ALIBI) { const float ab = -slope2 * (float)nrel - ((FLAGS & AF_ROBUST) ? 0.f : m);
; #pragma unroll
;                 for (int r = 0; r < 16; ++r) { const float c = (float)(16 * (r >> 3) + (r & 7)); p0[r] = __builtin_fmaf(slope2, c, ab); p1[r] = __builtin_fmaf(slope2, c + 32.f, ab); }
;             } else if (FLAGS & AF_ROBUST) {
; #pragma unroll
;                 for (int r = 0; r < 16; ++r) { p0[r] = 0.f; p1[r] = 0.f; }
;             } else { p0 = negm; p1 = negm; }
;             __builtin_amdgcn_sched_barrier(0);
; #pragma unroll
;             for (int c = 0; c < ND0 / 2; ++c) {
;                 if (c + 1 < ND0 / 2) {
; #pragma unroll
;                     for (int i = 0; i < 2; ++i) { kf[(c + 1) & 1][2 * i] = *(const LAS bf16x8*)(kb + (2 * c + 2 + i) * 32); kf[(c + 1) & 1][2 * i + 1] = *(const LAS bf16x8*)(kb + 32 * KROW + (2 * c + 2 + i) * 32); }
;                 }
; #pragma unroll
;                 for (int i = 0; i < 2; ++i) {
;                     p0 = __builtin_amdgcn_mfma_f32_32x32x16_bf16(kf[c & 1][2 * i], qr[2 * c + i], p0, 0, 0, 0);
;                     p1 = __builtin_amdgcn_mfma_f32_32x32x16_bf16(kf[c & 1][2 * i + 1], qr[2 * c + i], p1, 0, 0, 0);
;                 }
;                 __builtin_amdgcn_sched_barrier(0);
;             }
;     ...
;             f32x2 rs2 = {0.f, 0.f};
; #pragma unroll
;             for (int r = 0; r < 16; ++r) { p0[r] = __builtin_amdgcn_exp2f(p0[r]); p1[r] = __builtin_amdgcn_exp2f(p1[r]); }
; #pragma unroll
;             for (int r = 0; r < 16; r += 2) { rs2 += (f32x2){p0[r], p0[r + 1]}; rs2 += (f32x2){p1[r], p1[r + 1]}; }
;             l += rs2.x + rs2.y;
;             bf16x8 pf[4];
;             pf[0] = pack_bf16x8(p0, 0); pf[1] = pack_bf16x8(p0, 8); pf[2] = pack_bf16x8(p1, 0); pf[3] = pack_bf16x8(p1, 8);
.Ld_notfirst_q1:
	v_exp_f32_e32 v112, v112
	v_exp_f32_e32 v113, v113
	v_exp_f32_e32 v128, v128
	v_exp_f32_e32 v129, v129
	v_add_f32_e32 v240, v112, v199
	v_exp_f32_e32 v114, v114
	v_exp_f32_e32 v115, v115
	v_add_f32_e32 v240, v128, v240
	v_add_f32_e32 v241, v113, v129
	v_exp_f32_e32 v130, v130
	v_exp_f32_e32 v131, v131
	v_add_f32_e32 v240, v114, v240
	v_add_f32_e32 v241, v115, v241
	v_exp_f32_e32 v116, v116
	v_exp_f32_e32 v117, v117
	v_add_f32_e32 v240, v130, v240
	v_add_f32_e32 v241, v131, v241
	v_exp_f32_e32 v132, v132
	v_exp_f32_e32 v133, v133
	v_add_f32_e32 v240, v116, v240
	v_add_f32_e32 v241, v117, v241
	v_exp_f32_e32 v118, v118
	v_exp_f32_e32 v119, v119
	v_add_f32_e32 v240, v132, v240
	v_add_f32_e32 v241, v133, v241
	v_exp_f32_e32 v134, v134
	v_exp_f32_e32 v135, v135
	v_add_f32_e32 v240, v118, v240
	v_add_f32_e32 v241, v119, v241
	v_exp_f32_e32 v120, v120
	v_exp_f32_e32 v121, v121
	v_add_f32_e32 v240, v134, v240
	v_add_f32_e32 v241, v135, v241
	v_exp_f32_e32 v136, v136
	v_exp_f32_e32 v137, v137
	v_add_f32_e32 v240, v120, v240
	v_add_f32_e32 v241, v121, v241
	v_exp_f32_e32 v122, v122
	v_exp_f32_e32 v123, v123
	v_add_f32_e32 v240, v136, v240
	v_add_f32_e32 v241, v137, v241
	v_exp_f32_e32 v138, v138
	v_exp_f32_e32 v139, v139
	v_add_f32_e32 v240, v122, v240
	v_add_f32_e32 v241, v123, v241
	v_exp_f32_e32 v124, v124
	v_exp_f32_e32 v125, v125
	v_add_f32_e32 v240, v138, v240
	v_add_f32_e32 v241, v139, v241
	v_exp_f32_e32 v140, v140
	v_exp_f32_e32 v141, v141
	v_add_f32_e32 v240, v124, v240
	v_add_f32_e32 v241, v125, v241
	v_exp_f32_e32 v126, v126
	v_exp_f32_e32 v127, v127
	v_add_f32_e32 v240, v140, v240
	v_add_f32_e32 v241, v141, v241
	v_exp_f32_e32 v142, v142
	v_exp_f32_e32 v143, v143
	v_add_f32_e32 v240, v126, v240
	v_add_f32_e32 v241, v127, v241
	s_nop 0
	v_add_f32_e32 v240, v142, v240
	v_add_f32_e32 v241, v143, v241
	v_cvt_pk_bf16_f32 v112, v112, v113
	v_cvt_pk_bf16_f32 v113, v114, v115
	v_cvt_pk_bf16_f32 v114, v116, v117
	v_cvt_pk_bf16_f32 v115, v118, v119
	v_cvt_pk_bf16_f32 v116, v120, v121
	v_cvt_pk_bf16_f32 v117, v122, v123
	v_cvt_pk_bf16_f32 v118, v124, v125
	v_cvt_pk_bf16_f32 v119, v126, v127
	v_cvt_pk_bf16_f32 v120, v128, v129
	v_cvt_pk_bf16_f32 v121, v130, v131
	v_cvt_pk_bf16_f32 v122, v132, v133
	v_cvt_pk_bf16_f32 v123, v134, v135
	v_cvt_pk_bf16_f32 v124, v136, v137
	v_cvt_pk_bf16_f32 v125, v138, v139
	v_cvt_pk_bf16_f32 v126, v140, v141
	v_cvt_pk_bf16_f32 v127, v142, v143
	v_add_f32_e32 v199, v240, v241
.Ld_nosm_q1:
	s_add_i32 s13, s23, 1
	s_cmp_ge_i32 s13, s3
	s_cbranch_scc1 .Ld_noqk_q1
	s_cmp_lt_i32 s13, s24
	s_cbranch_scc1 .Ld_noqk_q1
	s_add_i32 s12, s23, 1
	s_and_b32 s12, s12, 3
	s_mulk_i32 s12, 0x6c00
	v_add3_u32 v247, s12, v201, v194
	ds_read_b128 v[160:163], v247 offset:0
	ds_read_b128 v[164:167], v247 offset:32
	ds_read_b128 v[168:171], v247 offset:64
	ds_read_b128 v[172:175], v247 offset:96
	ds_read_b128 v[224:227], v247 offset:4608
	ds_read_b128 v[228:231], v247 offset:4640
	ds_read_b128 v[232:235], v247 offset:4672
	ds_read_b128 v[236:239], v247 offset:4704
	v_add_u32_e32 v246, 64, v205
	v_cvt_f32_i32_e32 v246, v246
	v_fma_f32 v242, -v14, v246, -v222
	v_mov_b32_e32 v80, v242
	v_add_f32_e32 v81, v14, v242
	v_fma_f32 v82, v14, s62, v242
	v_fma_f32 v83, v14, s63, v242
	v_fma_f32 v84, v14, s64, v242
	v_fma_f32 v85, v14, s65, v242
	v_fma_f32 v86, v14, s66, v242
	v_fma_f32 v87, v14, s67, v242
	v_fma_f32 v88, v14, s68, v242
	v_fma_f32 v89, v14, s69, v242
	v_fma_f32 v90, v14, s70, v242
	v_fma_f32 v91, v14, s71, v242
	v_fma_f32 v92, v14, s72, v242
	v_fma_f32 v93, v14, s73, v242
	v_fma_f32 v94, v14, s76, v242
	v_fma_f32 v95, v14, s77, v242
	v_fma_f32 v96, v14, s8, v242
	v_fma_f32 v97, v14, s9, v242
	v_fma_f32 v98, v14, s96, v242
	v_fma_f32 v99, v14, s97, v242
	v_fma_f32 v100, v14, s94, v242
	v_fma_f32 v101, v14, s95, v242
	v_fma_f32 v102, v14, s92, v242
	v_fma_f32 v103, v14, s93, v242
	v_fma_f32 v104, v14, s90, v242
	v_fma_f32 v105, v14, s91, v242
	v_fma_f32 v106, v14, s88, v242
	v_fma_f32 v107, v14, s89, v242
	v_fma_f32 v108, v14, s86, v242
	v_fma_f32 v109, v14, s87, v242
	v_fma_f32 v110, v14, s78, v242
	v_fma_f32 v111, v14, s79, v242
	s_waitcnt lgkmcnt(0)
	v_mfma_f32_32x32x16_bf16 v[80:95], v[160:163], v[2:5], v[80:95]
	v_mfma_f32_32x32x16_bf16 v[96:111], v[224:227], v[2:5], v[96:111]
	v_mfma_f32_32x32x16_bf16 v[80:95], v[164:167], v[6:9], v[80:95]
	v_mfma_f32_32x32x16_bf16 v[96:111], v[228:231], v[6:9], v[96:111]
	v_mfma_f32_32x32x16_bf16 v[80:95], v[168:171], v[10:13], v[80:95]
	v_mfma_f32_32x32x16_bf16 v[96:111], v[232:235], v[10:13], v[96:111]
	v_mfma_f32_32x32x16_bf16 v[80:95], v[172:175], v[144:147], v[80:95]
	v_mfma_f32_32x32x16_bf16 v[96:111], v[236:239], v[144:147], v[96:111]

; #define LAS __attribute__((address_space(3)))
; template <int DQK, int DV, int FLAGS, int qp, int kp, int vts, int op> ...
;     ...
;             if (FLAGS & AF_ALIBI) { const float ab = -slope2 * (float)nrel - ((FLAGS & AF_ROBUST) ? 0.f : m);
; #pragma unroll
;                 for (int r = 0; r < 16; ++r) { const float c = (float)(16 * (r >> 3) + (r & 7)); p0[r] = __builtin_fmaf(slope2, c, ab); p1[r] = __builtin_fmaf(slope2, c + 32.f, ab); }
;             } else if (FLAGS & AF_ROBUST) {
; #pragma unroll
;                 for (int r = 0; r < 16; ++r) { p0[r] = 0.f; p1[r] = 0.f; }
;             } else { p0 = negm; p1 = negm; }
;             __builtin_amdgcn_sched_barrier(0);
; #pragma unroll
;             for (int c = 0; c < ND0 / 2; ++c) {
;                 if (c + 1 < ND0 / 2) {
; #pragma unroll
;                     for (int i = 0; i < 2; ++i) { kf[(c + 1) & 1][2 * i] = *(const LAS bf16x8*)(kb + (2 * c + 2 + i) * 32); kf[(c + 1) & 1][2 * i + 1] = *(const LAS bf16x8*)(kb + 32 * KROW + (2 * c + 2 + i) * 32); }
;                 }
; #pragma unroll
;                 for (int i = 0; i < 2; ++i) {
;                     p0 = __builtin_amdgcn_mfma_f32_32x32x16_bf16(kf[c & 1][2 * i], qr[2 * c + i], p0, 0, 0, 0);
;                     p1 = __builtin_amdgcn_mfma_f32_32x32x16_bf16(kf[c & 1][2 * i + 1], qr[2 * c + i], p1, 0, 0, 0);
;                 }
;                 __builtin_amdgcn_sched_barrier(0);
;             }
;             if (more) ATT_GLOAD((FLAGS & AF_REV) ? t - 1 : t + 1);
;     ...
;             f32x2 rs2 = {0.f, 0.f};
; #pragma unroll
;             for (int r = 0; r < 16; ++r) { p0[r] = __builtin_amdgcn_exp2f(p0[r]); p1[r] = __builtin_amdgcn_exp2f(p1[r]); }
; #pragma unroll
;             for (int r = 0; r < 16; r += 2) { rs2 += (f32x2){p0[r], p0[r + 1]}; rs2 += (f32x2){p1[r], p1[r + 1]}; }
;             l += rs2.x + rs2.y;
;             bf16x8 pf[4];
;             pf[0] = pack_bf16x8(p0, 0); pf[1] = pack_bf16x8(p0, 8); pf[2] = pack_bf16x8(p1, 0); pf[3] = pack_bf16x8(p1, 8);
;             __builtin_amdgcn_sched_barrier(0);
; #pragma unroll
;             for (int d = 0; d < NDB; ++d) {
;                 if (d + 1 < NDB) {
; #pragma unroll
;                     for (int ks = 0; ks < 4; ++ks) vf[(d + 1) & 1][ks] = *(const LAS bf16x8*)(vb + (d + 1) * 32 * VROW + ks * 32);
;                 }
; #pragma unroll
.Ld_top2:
	s_cmp_le_i32 s23, s24
	s_cbranch_scc1 .Ld_gen2
	s_add_i32 s13, s23, 1
	s_cmp_ge_i32 s13, s3
	s_cbranch_scc1 .Ld_gen2
	ds_read_b128 v[224:227], v251 offset:41472
	ds_read_b128 v[228:231], v251 offset:41504
	ds_read_b128 v[232:235], v251 offset:41536
	ds_read_b128 v[236:239], v251 offset:41568
	v_mfma_f32_32x32x16_bf16 v[64:79], v[160:163], v[112:115], v[64:79]
	v_exp_f32_e32 v80, v80
	v_exp_f32_e32 v81, v81
	v_exp_f32_e32 v96, v96
	v_exp_f32_e32 v97, v97
	v_add_u32_e32 v246, 64, v205
	v_mfma_f32_32x32x16_bf16 v[64:79], v[164:167], v[116:119], v[64:79]
	v_add_f32_e32 v240, v80, v199
	v_exp_f32_e32 v82, v82
	v_exp_f32_e32 v83, v83
	v_add_f32_e32 v240, v96, v240
	v_cvt_f32_i32_e32 v246, v246
	v_mfma_f32_32x32x16_bf16 v[64:79], v[168:171], v[120:123], v[64:79]
	v_add_f32_e32 v241, v81, v97
	v_exp_f32_e32 v98, v98
	v_exp_f32_e32 v99, v99
	v_add_f32_e32 v240, v82, v240
	v_fma_f32 v242, -v14, v246, -v222
	v_mfma_f32_32x32x16_bf16 v[64:79], v[172:175], v[124:127], v[64:79]
	v_add_f32_e32 v241, v83, v241
	v_exp_f32_e32 v84, v84
	v_exp_f32_e32 v85, v85
	v_add_f32_e32 v240, v98, v240
	v_fma_f32 v128, v14, s8, v242
	ds_read_b128 v[160:163], v251 offset:46080
	ds_read_b128 v[164:167], v251 offset:46112
	ds_read_b128 v[168:171], v251 offset:46144
	ds_read_b128 v[172:175], v251 offset:46176
	s_waitcnt lgkmcnt(4)
	v_mfma_f32_32x32x16_bf16 v[48:63], v[224:227], v[112:115], v[48:63]
	v_add_f32_e32 v241, v99, v241
	v_exp_f32_e32 v100, v100
	v_exp_f32_e32 v101, v101
	v_add_f32_e32 v240, v84, v240
	v_fma_f32 v129, v14, s9, v242
	s_waitcnt vmcnt(0)
	ds_write_b128 v204, v[148:151] offset:0
	v_mfma_f32_32x32x16_bf16 v[48:63], v[228:231], v[116:119], v[48:63]
	v_add_f32_e32 v241, v85, v241
	v_exp_f32_e32 v86, v86
	v_exp_f32_e32 v87, v87
	v_add_f32_e32 v240, v100, v240
	v_fma_f32 v130, v14, s96, v242
	ds_write_b128 v200, v[152:155] offset:9216
	v_mfma_f32_32x32x16_bf16 v[48:63], v[232:235], v[120:123], v[48:63]
	v_add_f32_e32 v241, v101, v241
	v_exp_f32_e32 v102, v102
	v_exp_f32_e32 v103, v103
	v_add_f32_e32 v240, v86, v240
	v_fma_f32 v131, v14, s97, v242
	ds_write_b128 v200, v[156:159] offset:18432
	v_mfma_f32_32x32x16_bf16 v[48:63], v[236:239], v[124:127], v[48:63]
	v_add_f32_e32 v241, v87, v241
	v_exp_f32_e32 v88, v88
	v_exp_f32_e32 v89, v89
	v_add_f32_e32 v240, v102, v240
	v_fma_f32 v132, v14, s94, v242
	ds_read_b128 v[224:227], v251 offset:50688
	ds_read_b128 v[228:231], v251 offset:50720
	ds_read_b128 v[232:235], v251 offset:50752
	ds_read_b128 v[236:239], v251 offset:50784
	s_waitcnt lgkmcnt(4)
	v_mfma_f32_32x32x16_bf16 v[32:47], v[160:163], v[112:115], v[32:47]
	v_add_f32_e32 v241, v103, v241
	v_exp_f32_e32 v104, v104
	v_exp_f32_e32 v105, v105
	v_add_f32_e32 v240, v88, v240
	v_fma_f32 v133, v14, s95, v242
	v_mfma_f32_32x32x16_bf16 v[32:47], v[164:167], v[116:119], v[32:47]
	v_add_f32_e32 v241, v89, v241
	v_exp_f32_e32 v90, v90
	v_exp_f32_e32 v91, v91
	v_add_f32_e32 v240, v104, v240
	v_fma_f32 v134, v14, s92, v242
	s_ashr_i32 s35, s34, 31
	s_lshl_b64 s[6:7], s[34:35], 17
	s_lshl_b64 s[10:11], s[34:35], 7
	s_add_u32 s10, s18, s10
	s_addc_u32 s11, s19, s11
	s_add_u32 s6, s6, s100
	s_addc_u32 s7, s7, s101
	global_load_dwordx4 v[148:151], v243, s[6:7]
	v_mfma_f32_32x32x16_bf16 v[32:47], v[168:171], v[120:123], v[32:47]
	v_add_f32_e32 v241, v105, v241
	v_exp_f32_e32 v106, v106
	v_exp_f32_e32 v107, v107
	v_add_f32_e32 v240, v90, v240
	v_fma_f32 v135, v14, s93, v242
	global_load_dwordx4 v[152:155], v0, s[10:11]
	v_mfma_f32_32x32x16_bf16 v[32:47], v[172:175], v[124:127], v[32:47]
	v_add_f32_e32 v241, v91, v241
	v_exp_f32_e32 v92, v92
	v_exp_f32_e32 v93, v93
	v_add_f32_e32 v240, v106, v240
	v_fma_f32 v136, v14, s90, v242
	global_load_dwordx4 v[156:159], v196, s[10:11]
	s_add_i32 s34, s34, -1
	ds_read_b128 v[160:163], v245 offset:32256
	ds_read_b128 v[164:167], v245 offset:32288
	ds_read_b128 v[168:171], v245 offset:32320
	ds_read_b128 v[172:175], v245 offset:32352
	s_waitcnt lgkmcnt(4)
	v_mfma_f32_32x32x16_bf16 v[16:31], v[224:227], v[112:115], v[16:31]
	v_add_f32_e32 v241, v107, v241
	v_exp_f32_e32 v108, v108
	v_exp_f32_e32 v109, v109
	v_add_f32_e32 v240, v92, v240
	v_fma_f32 v137, v14, s91, v242
	v_mfma_f32_32x32x16_bf16 v[16:31], v[228:231], v[116:119], v[16:31]
	v_add_f32_e32 v241, v93, v241
	v_exp_f32_e32 v94, v94
	v_exp_f32_e32 v95, v95
	v_add_f32_e32 v240, v108, v240
	v_fma_f32 v138, v14, s88, v242
	v_mfma_f32_32x32x16_bf16 v[16:31], v[232:235], v[120:123], v[16:31]
	v_add_f32_e32 v241, v109, v241
	v_exp_f32_e32 v110, v110
	v_exp_f32_e32 v111, v111
	v_add_f32_e32 v240, v94, v240
	v_fma_f32 v139, v14, s89, v242
	v_mfma_f32_32x32x16_bf16 v[16:31], v[236:239], v[124:127], v[16:31]
	v_add_f32_e32 v241, v95, v241
	v_fma_f32 v140, v14, s86, v242
	v_fma_f32 v141, v14, s87, v242
	v_fma_f32 v142, v14, s78, v242
	v_fma_f32 v143, v14, s79, v242
	ds_read_b128 v[224:227], v245 offset:27648
	ds_read_b128 v[228:231], v245 offset:27680
	ds_read_b128 v[232:235], v245 offset:27712
	ds_read_b128 v[236:239], v245 offset:27744
	s_waitcnt lgkmcnt(4)
	v_mfma_f32_32x32x16_bf16 v[128:143], v[160:163], v[2:5], v[128:143]
	v_mov_b32_e32 v112, v242
	v_add_f32_e32 v113, v14, v242
	v_fma_f32 v114, v14, s62, v242
	v_fma_f32 v115, v14, s63, v242
	v_mfma_f32_32x32x16_bf16 v[128:143], v[164:167], v[6:9], v[128:143]
	v_fma_f32 v116, v14, s64, v242
	v_fma_f32 v117, v14, s65, v242
	v_fma_f32 v118, v14, s66, v242
	v_fma_f32 v119, v14, s67, v242
	v_mfma_f32_32x32x16_bf16 v[128:143], v[168:171], v[10:13], v[128:143]
	v_fma_f32 v120, v14, s68, v242
	v_fma_f32 v121, v14, s69, v242
	v_fma_f32 v122, v14, s70, v242
	v_fma_f32 v123, v14, s71, v242
	v_mfma_f32_32x32x16_bf16 v[128:143], v[172:175], v[144:147], v[128:143]
	v_fma_f32 v124, v14, s72, v242
	v_fma_f32 v125, v14, s73, v242
	v_fma_f32 v126, v14, s76, v242
	v_fma_f32 v127, v14, s77, v242
	ds_read_b128 v[160:163], v250 offset:9216
	ds_read_b128 v[164:167], v250 offset:9248
	ds_read_b128 v[168:171], v250 offset:9280
	ds_read_b128 v[172:175], v250 offset:9312
	s_waitcnt lgkmcnt(4)
	v_mfma_f32_32x32x16_bf16 v[112:127], v[224:227], v[2:5], v[112:127]
	s_nop 0
	v_add_f32_e32 v240, v110, v240
	v_add_f32_e32 v241, v111, v241
	v_cvt_pk_bf16_f32 v80, v80, v81
	v_cvt_pk_bf16_f32 v81, v82, v83
	v_cvt_pk_bf16_f32 v82, v84, v85
	v_mfma_f32_32x32x16_bf16 v[112:127], v[228:231], v[6:9], v[112:127]
	v_cvt_pk_bf16_f32 v83, v86, v87
	v_cvt_pk_bf16_f32 v84, v88, v89
	v_cvt_pk_bf16_f32 v85, v90, v91
	v_cvt_pk_bf16_f32 v86, v92, v93
	v_cvt_pk_bf16_f32 v87, v94, v95
	v_cvt_pk_bf16_f32 v88, v96, v97
	v_mfma_f32_32x32x16_bf16 v[112:127], v[232:235], v[10:13], v[112:127]
	v_cvt_pk_bf16_f32 v89, v98, v99
	v_cvt_pk_bf16_f32 v90, v100, v101
	v_cvt_pk_bf16_f32 v91, v102, v103
	v_cvt_pk_bf16_f32 v92, v104, v105
	v_cvt_pk_bf16_f32 v93, v106, v107
	v_cvt_pk_bf16_f32 v94, v108, v109
	v_mfma_f32_32x32x16_bf16 v[112:127], v[236:239], v[144:147], v[112:127]
	v_cvt_pk_bf16_f32 v95, v110, v111
	v_add_f32_e32 v199, v240, v241
	s_branch .Ld_tail2

; #define LAS __attribute__((address_space(3)))
; template <int DQK, int DV, int FLAGS, int qp, int kp, int vts, int op> ...
;     ...
;             if (FLAGS & AF_ALIBI) { const float ab = -slope2 * (float)nrel - ((FLAGS & AF_ROBUST) ? 0.f : m);
; #pragma unroll
;                 for (int r = 0; r < 16; ++r) { const float c = (float)(16 * (r >> 3) + (r & 7)); p0[r] = __builtin_fmaf(slope2, c, ab); p1[r] = __builtin_fmaf(slope2, c + 32.f, ab); }
;             } else if (FLAGS & AF_ROBUST) {
; #pragma unroll
;                 for (int r = 0; r < 16; ++r) { p0[r] = 0.f; p1[r] = 0.f; }
;             } else { p0 = negm; p1 = negm; }
;             __builtin_amdgcn_sched_barrier(0);
; #pragma unroll
;             for (int c = 0; c < ND0 / 2; ++c) {
;                 if (c + 1 < ND0 / 2) {
; #pragma unroll
;                     for (int i = 0; i < 2; ++i) { kf[(c + 1) & 1][2 * i] = *(const LAS bf16x8*)(kb + (2 * c + 2 + i) * 32); kf[(c + 1) & 1][2 * i + 1] = *(const LAS bf16x8*)(kb + 32 * KROW + (2 * c + 2 + i) * 32); }
;                 }
; #pragma unroll
;                 for (int i = 0; i < 2; ++i) {
;                     p0 = __builtin_amdgcn_mfma_f32_32x32x16_bf16(kf[c & 1][2 * i], qr[2 * c + i], p0, 0, 0, 0);
;                     p1 = __builtin_amdgcn_mfma_f32_32x32x16_bf16(kf[c & 1][2 * i + 1], qr[2 * c + i], p1, 0, 0, 0);
;                 }
;                 __builtin_amdgcn_sched_barrier(0);
;             }
;             if (more) ATT_GLOAD((FLAGS & AF_REV) ? t - 1 : t + 1);
;     ...
;             f32x2 rs2 = {0.f, 0.f};
; #pragma unroll
;             for (int r = 0; r < 16; ++r) { p0[r] = __builtin_amdgcn_exp2f(p0[r]); p1[r] = __builtin_amdgcn_exp2f(p1[r]); }
; #pragma unroll
;             for (int r = 0; r < 16; r += 2) { rs2 += (f32x2){p0[r], p0[r + 1]}; rs2 += (f32x2){p1[r], p1[r + 1]}; }
;             l += rs2.x + rs2.y;
;             bf16x8 pf[4];
;             pf[0] = pack_bf16x8(p0, 0); pf[1] = pack_bf16x8(p0, 8); pf[2] = pack_bf16x8(p1, 0); pf[3] = pack_bf16x8(p1, 8);
;             __builtin_amdgcn_sched_barrier(0);
; #pragma unroll
;             for (int d = 0; d < NDB; ++d) {
;                 if (d + 1 < NDB) {
; #pragma unroll
;                     for (int ks = 0; ks < 4; ++ks) vf[(d + 1) & 1][ks] = *(const LAS bf16x8*)(vb + (d + 1) * 32 * VROW + ks * 32);
;                 }
; #pragma unroll
.Ld_top3:
	s_cmp_le_i32 s23, s24
	s_cbranch_scc1 .Ld_gen3
	s_add_i32 s13, s23, 1
	s_cmp_ge_i32 s13, s3
	s_cbranch_scc1 .Ld_gen3
	ds_read_b128 v[224:227], v250 offset:13824
	ds_read_b128 v[228:231], v250 offset:13856
	ds_read_b128 v[232:235], v250 offset:13888
	ds_read_b128 v[236:239], v250 offset:13920
	v_mfma_f32_32x32x16_bf16 v[64:79], v[160:163], v[80:83], v[64:79]
	v_exp_f32_e32 v112, v112
	v_exp_f32_e32 v113, v113
	v_exp_f32_e32 v128, v128
	v_exp_f32_e32 v129, v129
	v_add_u32_e32 v246, 64, v205
	v_mfma_f32_32x32x16_bf16 v[64:79], v[164:167], v[84:87], v[64:79]
	v_add_f32_e32 v240, v112, v199
	v_exp_f32_e32 v114, v114
	v_exp_f32_e32 v115, v115
	v_add_f32_e32 v240, v128, v240
	v_cvt_f32_i32_e32 v246, v246
	v_mfma_f32_32x32x16_bf16 v[64:79], v[168:171], v[88:91], v[64:79]
	v_add_f32_e32 v241, v113, v129
	v_exp_f32_e32 v130, v130
	v_exp_f32_e32 v131, v131
	v_add_f32_e32 v240, v114, v240
	v_fma_f32 v242, -v14, v246, -v222
	v_mfma_f32_32x32x16_bf16 v[64:79], v[172:175], v[92:95], v[64:79]
	v_add_f32_e32 v241, v115, v241
	v_exp_f32_e32 v116, v116
	v_exp_f32_e32 v117, v117
	v_add_f32_e32 v240, v130, v240
	v_fma_f32 v96, v14, s8, v242
	ds_read_b128 v[160:163], v250 offset:18432
	ds_read_b128 v[164:167], v250 offset:18464
	ds_read_b128 v[168:171], v250 offset:18496
	ds_read_b128 v[172:175], v250 offset:18528
	s_waitcnt lgkmcnt(4)
	v_mfma_f32_32x32x16_bf16 v[48:63], v[224:227], v[80:83], v[48:63]
	v_add_f32_e32 v241, v131, v241
	v_exp_f32_e32 v132, v132
	v_exp_f32_e32 v133, v133
	v_add_f32_e32 v240, v116, v240
	v_fma_f32 v97, v14, s9, v242
	s_waitcnt vmcnt(0)
	ds_write_b128 v204, v[148:151] offset:27648
	v_mfma_f32_32x32x16_bf16 v[48:63], v[228:231], v[84:87], v[48:63]
	v_add_f32_e32 v241, v117, v241
	v_exp_f32_e32 v118, v118
	v_exp_f32_e32 v119, v119
	v_add_f32_e32 v240, v132, v240
	v_fma_f32 v98, v14, s96, v242
	ds_write_b128 v200, v[152:155] offset:36864
	v_mfma_f32_32x32x16_bf16 v[48:63], v[232:235], v[88:91], v[48:63]
	v_add_f32_e32 v241, v133, v241
	v_exp_f32_e32 v134, v134
	v_exp_f32_e32 v135, v135
	v_add_f32_e32 v240, v118, v240
	v_fma_f32 v99, v14, s97, v242
	ds_write_b128 v200, v[156:159] offset:46080
	v_mfma_f32_32x32x16_bf16 v[48:63], v[236:239], v[92:95], v[48:63]
	v_add_f32_e32 v241, v119, v241
	v_exp_f32_e32 v120, v120
	v_exp_f32_e32 v121, v121
	v_add_f32_e32 v240, v134, v240
	v_fma_f32 v100, v14, s94, v242
	ds_read_b128 v[224:227], v250 offset:23040
	ds_read_b128 v[228:231], v250 offset:23072
	ds_read_b128 v[232:235], v250 offset:23104
	ds_read_b128 v[236:239], v250 offset:23136
	s_waitcnt lgkmcnt(4)
	v_mfma_f32_32x32x16_bf16 v[32:47], v[160:163], v[80:83], v[32:47]
	v_add_f32_e32 v241, v135, v241
	v_exp_f32_e32 v136, v136
	v_exp_f32_e32 v137, v137
	v_add_f32_e32 v240, v120, v240
	v_fma_f32 v101, v14, s95, v242
	v_mfma_f32_32x32x16_bf16 v[32:47], v[164:167], v[84:87], v[32:47]
	v_add_f32_e32 v241, v121, v241
	v_exp_f32_e32 v122, v122
	v_exp_f32_e32 v123, v123
	v_add_f32_e32 v240, v136, v240
	v_fma_f32 v102, v14, s92, v242
	s_ashr_i32 s35, s34, 31
	s_lshl_b64 s[6:7], s[34:35], 17
	s_lshl_b64 s[10:11], s[34:35], 7
	s_add_u32 s10, s18, s10
	s_addc_u32 s11, s19, s11
	s_add_u32 s6, s6, s100
	s_addc_u32 s7, s7, s101
	global_load_dwordx4 v[148:151], v243, s[6:7]
	v_mfma_f32_32x32x16_bf16 v[32:47], v[168:171], v[88:91], v[32:47]
	v_add_f32_e32 v241, v137, v241
	v_exp_f32_e32 v138, v138
	v_exp_f32_e32 v139, v139
	v_add_f32_e32 v240, v122, v240
	v_fma_f32 v103, v14, s93, v242
	global_load_dwordx4 v[152:155], v0, s[10:11]
	v_mfma_f32_32x32x16_bf16 v[32:47], v[172:175], v[92:95], v[32:47]
	v_add_f32_e32 v241, v123, v241
	v_exp_f32_e32 v124, v124
	v_exp_f32_e32 v125, v125
	v_add_f32_e32 v240, v138, v240
	v_fma_f32 v104, v14, s90, v242
	global_load_dwordx4 v[156:159], v196, s[10:11]
	s_add_i32 s34, s34, -1
	ds_read_b128 v[160:163], v244 offset:4608
	ds_read_b128 v[164:167], v244 offset:4640
	ds_read_b128 v[168:171], v244 offset:4672
	ds_read_b128 v[172:175], v244 offset:4704
	s_waitcnt lgkmcnt(4)
	v_mfma_f32_32x32x16_bf16 v[16:31], v[224:227], v[80:83], v[16:31]
	v_add_f32_e32 v241, v139, v241
	v_exp_f32_e32 v140, v140
	v_exp_f32_e32 v141, v141
	v_add_f32_e32 v240, v124, v240
	v_fma_f32 v105, v14, s91, v242
	v_mfma_f32_32x32x16_bf16 v[16:31], v[228:231], v[84:87], v[16:31]
	v_add_f32_e32 v241, v125, v241
	v_exp_f32_e32 v126, v126
	v_exp_f32_e32 v127, v127
	v_add_f32_e32 v240, v140, v240
	v_fma_f32 v106, v14, s88, v242
	v_mfma_f32_32x32x16_bf16 v[16:31], v[232:235], v[88:91], v[16:31]
	v_add_f32_e32 v241, v141, v241
	v_exp_f32_e32 v142, v142
	v_exp_f32_e32 v143, v143
	v_add_f32_e32 v240, v126, v240
	v_fma_f32 v107, v14, s89, v242
	v_mfma_f32_32x32x16_bf16 v[16:31], v[236:239], v[92:95], v[16:31]
	v_add_f32_e32 v241, v127, v241
	v_fma_f32 v108, v14, s86, v242
	v_fma_f32 v109, v14, s87, v242
	v_fma_f32 v110, v14, s78, v242
	v_fma_f32 v111, v14, s79, v242
	ds_read_b128 v[224:227], v244 offset:0
	ds_read_b128 v[228:231], v244 offset:32
	ds_read_b128 v[232:235], v244 offset:64
	ds_read_b128 v[236:239], v244 offset:96
	s_waitcnt lgkmcnt(4)
	v_mfma_f32_32x32x16_bf16 v[96:111], v[160:163], v[2:5], v[96:111]
	v_mov_b32_e32 v80, v242
	v_add_f32_e32 v81, v14, v242
	v_fma_f32 v82, v14, s62, v242
	v_fma_f32 v83, v14, s63, v242
	v_mfma_f32_32x32x16_bf16 v[96:111], v[164:167], v[6:9], v[96:111]
	v_fma_f32 v84, v14, s64, v242
	v_fma_f32 v85, v14, s65, v242
	v_fma_f32 v86, v14, s66, v242
	v_fma_f32 v87, v14, s67, v242
	v_mfma_f32_32x32x16_bf16 v[96:111], v[168:171], v[10:13], v[96:111]
	v_fma_f32 v88, v14, s68, v242
	v_fma_f32 v89, v14, s69, v242
	v_fma_f32 v90, v14, s70, v242
	v_fma_f32 v91, v14, s71, v242
	v_mfma_f32_32x32x16_bf16 v[96:111], v[172:175], v[144:147], v[96:111]
	v_fma_f32 v92, v14, s72, v242
	v_fma_f32 v93, v14, s73, v242
	v_fma_f32 v94, v14, s76, v242
	v_fma_f32 v95, v14, s77, v242
	ds_read_b128 v[160:163], v250 offset:36864
	ds_read_b128 v[164:167], v250 offset:36896
	ds_read_b128 v[168:171], v250 offset:36928
	ds_read_b128 v[172:175], v250 offset:36960
	s_waitcnt lgkmcnt(4)
	v_mfma_f32_32x32x16_bf16 v[80:95], v[224:227], v[2:5], v[80:95]
	s_nop 0
	v_add_f32_e32 v240, v142, v240
	v_add_f32_e32 v241, v143, v241
	v_cvt_pk_bf16_f32 v112, v112, v113
	v_cvt_pk_bf16_f32 v113, v114, v115
	v_cvt_pk_bf16_f32 v114, v116, v117
	v_mfma_f32_32x32x16_bf16 v[80:95], v[228:231], v[6:9], v[80:95]
	v_cvt_pk_bf16_f32 v115, v118, v119
	v_cvt_pk_bf16_f32 v116, v120, v121
	v_cvt_pk_bf16_f32 v117, v122, v123
	v_cvt_pk_bf16_f32 v118, v124, v125
	v_cvt_pk_bf16_f32 v119, v126, v127
	v_cvt_pk_bf16_f32 v120, v128, v129
	v_mfma_f32_32x32x16_bf16 v[80:95], v[232:235], v[10:13], v[80:95]
	v_cvt_pk_bf16_f32 v121, v130, v131
	v_cvt_pk_bf16_f32 v122, v132, v133
	v_cvt_pk_bf16_f32 v123, v134, v135
	v_cvt_pk_bf16_f32 v124, v136, v137
	v_cvt_pk_bf16_f32 v125, v138, v139
	v_cvt_pk_bf16_f32 v126, v140, v141
	v_mfma_f32_32x32x16_bf16 v[80:95], v[236:239], v[144:147], v[80:95]
	v_cvt_pk_bf16_f32 v127, v142, v143
	v_add_f32_e32 v199, v240, v241
	s_branch .Ld_tail3

; #define LAS __attribute__((address_space(3)))
; template <int DQK, int DV, int FLAGS, int qp, int kp, int vts, int op> ...
;     ...
; #pragma unroll
;             for (int d = 0; d < NDB; ++d) {
;                 if (d + 1 < NDB) {
; #pragma unroll
;                     for (int ks = 0; ks < 4; ++ks) vf[(d + 1) & 1][ks] = *(const LAS bf16x8*)(vb + (d + 1) * 32 * VROW + ks * 32);
;                 }
; #pragma unroll
;                 for (int ks = 0; ks < 4; ++ks) o[d] = __builtin_amdgcn_mfma_f32_32x32x16_bf16(vf[d & 1][ks], pf[ks], o[d], 0, 0, 0);
;                 __builtin_amdgcn_sched_barrier(0);
;             }
.Ld_flush0:
	s_waitcnt lgkmcnt(0)
	s_add_i32 s12, s23, -1
	s_and_b32 s12, s12, 3
	s_mulk_i32 s12, 0x6c00
	v_add3_u32 v246, s12, v203, v194
	ds_read_b128 v[224:227], v246 offset:13824
	ds_read_b128 v[228:231], v246 offset:13856
	ds_read_b128 v[232:235], v246 offset:13888
	ds_read_b128 v[236:239], v246 offset:13920
	v_mfma_f32_32x32x16_bf16 v[64:79], v[160:163], v[112:115], v[64:79]
	v_mfma_f32_32x32x16_bf16 v[64:79], v[164:167], v[116:119], v[64:79]
	v_mfma_f32_32x32x16_bf16 v[64:79], v[168:171], v[120:123], v[64:79]
	v_mfma_f32_32x32x16_bf16 v[64:79], v[172:175], v[124:127], v[64:79]
	ds_read_b128 v[160:163], v246 offset:18432
	ds_read_b128 v[164:167], v246 offset:18464
	ds_read_b128 v[168:171], v246 offset:18496
	ds_read_b128 v[172:175], v246 offset:18528
	s_waitcnt lgkmcnt(4)
	v_mfma_f32_32x32x16_bf16 v[48:63], v[224:227], v[112:115], v[48:63]
	v_mfma_f32_32x32x16_bf16 v[48:63], v[228:231], v[116:119], v[48:63]
	v_mfma_f32_32x32x16_bf16 v[48:63], v[232:235], v[120:123], v[48:63]
	v_mfma_f32_32x32x16_bf16 v[48:63], v[236:239], v[124:127], v[48:63]
	ds_read_b128 v[224:227], v246 offset:23040
	ds_read_b128 v[228:231], v246 offset:23072
	ds_read_b128 v[232:235], v246 offset:23104
	ds_read_b128 v[236:239], v246 offset:23136
	s_waitcnt lgkmcnt(4)
	v_mfma_f32_32x32x16_bf16 v[32:47], v[160:163], v[112:115], v[32:47]
	v_mfma_f32_32x32x16_bf16 v[32:47], v[164:167], v[116:119], v[32:47]
	v_mfma_f32_32x32x16_bf16 v[32:47], v[168:171], v[120:123], v[32:47]
	v_mfma_f32_32x32x16_bf16 v[32:47], v[172:175], v[124:127], v[32:47]
	s_waitcnt lgkmcnt(0)
	v_mfma_f32_32x32x16_bf16 v[16:31], v[224:227], v[112:115], v[16:31]
	v_mfma_f32_32x32x16_bf16 v[16:31], v[228:231], v[116:119], v[16:31]
	v_mfma_f32_32x32x16_bf16 v[16:31], v[232:235], v[120:123], v[16:31]
	v_mfma_f32_32x32x16_bf16 v[16:31], v[236:239], v[124:127], v[16:31]
	s_branch .LBB0_957
.Ld_flush1:
	s_waitcnt lgkmcnt(0)
	s_add_i32 s12, s23, -1
	s_and_b32 s12, s12, 3
	s_mulk_i32 s12, 0x6c00
	v_add3_u32 v246, s12, v203, v194
	ds_read_b128 v[224:227], v246 offset:13824
	ds_read_b128 v[228:231], v246 offset:13856
	ds_read_b128 v[232:235], v246 offset:13888
	ds_read_b128 v[236:239], v246 offset:13920
	v_mfma_f32_32x32x16_bf16 v[64:79], v[160:163], v[80:83], v[64:79]
	v_mfma_f32_32x32x16_bf16 v[64:79], v[164:167], v[84:87], v[64:79]
	v_mfma_f32_32x32x16_bf16 v[64:79], v[168:171], v[88:91], v[64:79]
	v_mfma_f32_32x32x16_bf16 v[64:79], v[172:175], v[92:95], v[64:79]
	ds_read_b128 v[160:163], v246 offset:18432
	ds_read_b128 v[164:167], v246 offset:18464
	ds_read_b128 v[168:171], v246 offset:18496
	ds_read_b128 v[172:175], v246 offset:18528
	s_waitcnt lgkmcnt(4)
	v_mfma_f32_32x32x16_bf16 v[48:63], v[224:227], v[80:83], v[48:63]
	v_mfma_f32_32x32x16_bf16 v[48:63], v[228:231], v[84:87], v[48:63]
	v_mfma_f32_32x32x16_bf16 v[48:63], v[232:235], v[88:91], v[48:63]
	v_mfma_f32_32x32x16_bf16 v[48:63], v[236:239], v[92:95], v[48:63]
	ds_read_b128 v[224:227], v246 offset:23040
	ds_read_b128 v[228:231], v246 offset:23072
	ds_read_b128 v[232:235], v246 offset:23104
	ds_read_b128 v[236:239], v246 offset:23136
	s_waitcnt lgkmcnt(4)
	v_mfma_f32_32x32x16_bf16 v[32:47], v[160:163], v[80:83], v[32:47]
	v_mfma_f32_32x32x16_bf16 v[32:47], v[164:167], v[84:87], v[32:47]
	v_mfma_f32_32x32x16_bf16 v[32:47], v[168:171], v[88:91], v[32:47]
	v_mfma_f32_32x32x16_bf16 v[32:47], v[172:175], v[92:95], v[32:47]
	s_waitcnt lgkmcnt(0)
	v_mfma_f32_32x32x16_bf16 v[16:31], v[224:227], v[80:83], v[16:31]
	v_mfma_f32_32x32x16_bf16 v[16:31], v[228:231], v[84:87], v[16:31]
	v_mfma_f32_32x32x16_bf16 v[16:31], v[232:235], v[88:91], v[16:31]
	v_mfma_f32_32x32x16_bf16 v[16:31], v[236:239], v[92:95], v[16:31]
	s_branch .LBB0_957
